# static priority raise for waves 4-7 never reset (no s_setprio 0 at K-loop exits): epilogues, heads and later phases also run with waves 4-7 raised
# speedup vs baseline: 1.0102x; 1.0102x over previous
.Lkprio_5:
.LBB0_57:
	s_add_u32 s22, s0, 0xfffc0080
	s_addc_u32 s23, s1, -1
	s_add_i32 s65, 0, 0x10000
	v_add_u32_e32 v142, s65, v178
	ds_read_b128 v[130:133], v142
	ds_read_b128 v[134:137], v142 offset:1024
	ds_read_b128 v[138:141], v142 offset:2048
	ds_read_b128 v[142:145], v142 offset:3072
	s_cmp_eq_u32 s64, 12
	s_cselect_b32 s49, s37, s23
	s_cselect_b32 s48, s60, s22
	s_cselect_b32 s23, s35, s63
	s_cselect_b32 s22, s61, s62
	v_lshl_add_u64 v[186:187], s[0:1], 0, v[168:169]
	s_add_i32 m0, s47, 0xc000
	ds_read_b128 v[172:175], v180
	ds_read_b128 v[182:185], v180 offset:1024
	ds_read_b128 v[206:209], v180 offset:2048
	ds_read_b128 v[210:213], v180 offset:3072
	ds_read_b128 v[214:217], v180 offset:4096
	ds_read_b128 v[218:221], v180 offset:5120
	ds_read_b128 v[222:225], v180 offset:6144
	ds_read_b128 v[226:229], v180 offset:7168
	global_load_lds_dwordx4 v[186:187], off
	v_lshl_add_u64 v[186:187], s[0:1], 0, v[170:171]
	s_add_i32 m0, s47, 0xe000
	s_nop 0
	global_load_lds_dwordx4 v[186:187], off
	s_waitcnt lgkmcnt(8)
	s_barrier
	s_waitcnt lgkmcnt(0)
	v_mfma_f32_16x16x32_bf16 v[126:129], v[130:133], v[172:175], v[126:129]
	v_mfma_f32_16x16x32_bf16 v[122:125], v[138:141], v[172:175], v[122:125]
	v_mfma_f32_16x16x32_bf16 v[114:117], v[130:133], v[206:209], v[114:117]
	v_mfma_f32_16x16x32_bf16 v[106:109], v[138:141], v[206:209], v[106:109]
	v_mfma_f32_16x16x32_bf16 v[98:101], v[130:133], v[214:217], v[98:101]
	v_mfma_f32_16x16x32_bf16 v[90:93], v[138:141], v[214:217], v[90:93]
	v_mfma_f32_16x16x32_bf16 v[82:85], v[130:133], v[222:225], v[82:85]
	v_mfma_f32_16x16x32_bf16 v[74:77], v[138:141], v[222:225], v[74:77]
	v_mfma_f32_16x16x32_bf16 v[126:129], v[134:137], v[182:185], v[126:129]
	v_mfma_f32_16x16x32_bf16 v[122:125], v[142:145], v[182:185], v[122:125]
	v_mfma_f32_16x16x32_bf16 v[114:117], v[134:137], v[210:213], v[114:117]
	v_mfma_f32_16x16x32_bf16 v[106:109], v[142:145], v[210:213], v[106:109]
	v_mfma_f32_16x16x32_bf16 v[98:101], v[134:137], v[218:221], v[98:101]
	v_mfma_f32_16x16x32_bf16 v[90:93], v[142:145], v[218:221], v[90:93]
	v_mfma_f32_16x16x32_bf16 v[82:85], v[134:137], v[226:229], v[82:85]
	v_mfma_f32_16x16x32_bf16 v[74:77], v[142:145], v[226:229], v[74:77]
	s_barrier
	s_add_i32 s68, 0, 0x14000
	s_add_i32 s65, s65, s27
	v_add_u32_e32 v181, s68, v178
	v_lshl_add_u64 v[186:187], s[22:23], 0, v[0:1]
	s_mov_b32 m0, s65
	ds_read_b128 v[230:233], v181
	ds_read_b128 v[234:237], v181 offset:1024
	ds_read_b128 v[238:241], v181 offset:2048
	ds_read_b128 v[242:245], v181 offset:3072
	global_load_lds_dwordx4 v[186:187], off
	v_lshl_add_u64 v[246:247], s[22:23], 0, v[166:167]
	s_add_i32 m0, s65, 0x2000
	s_nop 0
	global_load_lds_dwordx4 v[246:247], off
	s_barrier
	s_waitcnt lgkmcnt(0)
	v_mfma_f32_16x16x32_bf16 v[118:121], v[230:233], v[172:175], v[118:121]
	v_mfma_f32_16x16x32_bf16 v[110:113], v[238:241], v[172:175], v[110:113]
	v_mfma_f32_16x16x32_bf16 v[102:105], v[230:233], v[206:209], v[102:105]
	v_mfma_f32_16x16x32_bf16 v[94:97], v[238:241], v[206:209], v[94:97]
	v_mfma_f32_16x16x32_bf16 v[86:89], v[230:233], v[214:217], v[86:89]
	v_mfma_f32_16x16x32_bf16 v[78:81], v[238:241], v[214:217], v[78:81]
	v_mfma_f32_16x16x32_bf16 v[70:73], v[230:233], v[222:225], v[70:73]
	v_mfma_f32_16x16x32_bf16 v[66:69], v[238:241], v[222:225], v[66:69]
	v_mfma_f32_16x16x32_bf16 v[118:121], v[234:237], v[182:185], v[118:121]
	v_mfma_f32_16x16x32_bf16 v[110:113], v[242:245], v[182:185], v[110:113]
	v_mfma_f32_16x16x32_bf16 v[102:105], v[234:237], v[210:213], v[102:105]
	v_mfma_f32_16x16x32_bf16 v[94:97], v[242:245], v[210:213], v[94:97]
	v_mfma_f32_16x16x32_bf16 v[86:89], v[234:237], v[218:221], v[86:89]
	v_mfma_f32_16x16x32_bf16 v[78:81], v[242:245], v[218:221], v[78:81]
	v_mfma_f32_16x16x32_bf16 v[70:73], v[234:237], v[226:229], v[70:73]
	v_mfma_f32_16x16x32_bf16 v[66:69], v[242:245], v[226:229], v[66:69]
	s_barrier
	s_mov_b32 m0, s47
	v_lshl_add_u64 v[248:249], s[48:49], 0, v[162:163]
	ds_read_b128 v[172:175], v180 offset:16384
	ds_read_b128 v[182:185], v180 offset:17408
	ds_read_b128 v[206:209], v180 offset:18432
	ds_read_b128 v[210:213], v180 offset:19456
	ds_read_b128 v[214:217], v180 offset:20480
	ds_read_b128 v[218:221], v180 offset:21504
	ds_read_b128 v[222:225], v180 offset:22528
	ds_read_b128 v[226:229], v180 offset:23552
	global_load_lds_dwordx4 v[248:249], off
	v_lshl_add_u64 v[250:251], s[48:49], 0, v[164:165]
	s_mov_b32 m0, s50
	s_nop 0
	global_load_lds_dwordx4 v[250:251], off
	s_barrier
	s_waitcnt lgkmcnt(0)
	v_mfma_f32_16x16x32_bf16 v[62:65], v[130:133], v[172:175], v[62:65]
	v_mfma_f32_16x16x32_bf16 v[58:61], v[138:141], v[172:175], v[58:61]
	v_mfma_f32_16x16x32_bf16 v[50:53], v[130:133], v[206:209], v[50:53]
	v_mfma_f32_16x16x32_bf16 v[42:45], v[138:141], v[206:209], v[42:45]
	v_mfma_f32_16x16x32_bf16 v[34:37], v[130:133], v[214:217], v[34:37]
	v_mfma_f32_16x16x32_bf16 v[26:29], v[138:141], v[214:217], v[26:29]
	v_mfma_f32_16x16x32_bf16 v[18:21], v[130:133], v[222:225], v[18:21]
	v_mfma_f32_16x16x32_bf16 v[10:13], v[138:141], v[222:225], v[10:13]
	v_mfma_f32_16x16x32_bf16 v[62:65], v[134:137], v[182:185], v[62:65]
	v_mfma_f32_16x16x32_bf16 v[58:61], v[142:145], v[182:185], v[58:61]
	v_mfma_f32_16x16x32_bf16 v[50:53], v[134:137], v[210:213], v[50:53]
	v_mfma_f32_16x16x32_bf16 v[42:45], v[142:145], v[210:213], v[42:45]
	v_mfma_f32_16x16x32_bf16 v[34:37], v[134:137], v[218:221], v[34:37]
	v_mfma_f32_16x16x32_bf16 v[26:29], v[142:145], v[218:221], v[26:29]
	v_mfma_f32_16x16x32_bf16 v[18:21], v[134:137], v[226:229], v[18:21]
	v_mfma_f32_16x16x32_bf16 v[10:13], v[142:145], v[226:229], v[10:13]
	s_barrier
	s_add_u32 s66, s22, 0x40000
	s_addc_u32 s67, s23, 0
	s_add_i32 s65, s68, s27
	v_lshl_add_u64 v[130:131], s[66:67], 0, v[0:1]
	s_mov_b32 m0, s65
	s_nop 0
	global_load_lds_dwordx4 v[130:131], off
	v_lshl_add_u64 v[130:131], s[66:67], 0, v[166:167]
	s_add_i32 m0, s65, 0x2000
	s_nop 0
	global_load_lds_dwordx4 v[130:131], off
	s_waitcnt vmcnt(6)
	s_barrier
	v_mfma_f32_16x16x32_bf16 v[54:57], v[230:233], v[172:175], v[54:57]
	v_mfma_f32_16x16x32_bf16 v[46:49], v[238:241], v[172:175], v[46:49]
	v_mfma_f32_16x16x32_bf16 v[38:41], v[230:233], v[206:209], v[38:41]
	v_mfma_f32_16x16x32_bf16 v[30:33], v[238:241], v[206:209], v[30:33]
	v_mfma_f32_16x16x32_bf16 v[22:25], v[230:233], v[214:217], v[22:25]
	v_mfma_f32_16x16x32_bf16 v[14:17], v[238:241], v[214:217], v[14:17]
	v_mfma_f32_16x16x32_bf16 v[6:9], v[230:233], v[222:225], v[6:9]
	v_mfma_f32_16x16x32_bf16 v[2:5], v[238:241], v[222:225], v[2:5]
	v_mfma_f32_16x16x32_bf16 v[54:57], v[234:237], v[182:185], v[54:57]
	v_mfma_f32_16x16x32_bf16 v[46:49], v[242:245], v[182:185], v[46:49]
	v_mfma_f32_16x16x32_bf16 v[38:41], v[234:237], v[210:213], v[38:41]
	v_mfma_f32_16x16x32_bf16 v[30:33], v[242:245], v[210:213], v[30:33]
	v_mfma_f32_16x16x32_bf16 v[22:25], v[234:237], v[218:221], v[22:25]
	v_mfma_f32_16x16x32_bf16 v[14:17], v[242:245], v[218:221], v[14:17]
	v_mfma_f32_16x16x32_bf16 v[6:9], v[234:237], v[226:229], v[6:9]
	v_mfma_f32_16x16x32_bf16 v[2:5], v[242:245], v[226:229], v[2:5]
	s_barrier
	s_add_i32 s65, 0, 0x18000
	v_add_u32_e32 v142, s65, v178
	ds_read_b128 v[130:133], v142
	ds_read_b128 v[134:137], v142 offset:1024
	ds_read_b128 v[138:141], v142 offset:2048
	ds_read_b128 v[142:145], v142 offset:3072
	s_add_u32 s48, s48, 0x40000
	s_addc_u32 s49, s49, 0
	s_mov_b32 m0, s51
	v_lshl_add_u64 v[230:231], s[48:49], 0, v[162:163]
	ds_read_b128 v[172:175], v180 offset:32768
	ds_read_b128 v[182:185], v180 offset:33792
	ds_read_b128 v[206:209], v180 offset:34816
	ds_read_b128 v[210:213], v180 offset:35840
	ds_read_b128 v[214:217], v180 offset:36864
	ds_read_b128 v[218:221], v180 offset:37888
	ds_read_b128 v[222:225], v180 offset:38912
	ds_read_b128 v[226:229], v180 offset:39936
	global_load_lds_dwordx4 v[230:231], off
	v_lshl_add_u64 v[230:231], s[48:49], 0, v[164:165]
	s_mov_b32 m0, s54
	s_nop 0
	global_load_lds_dwordx4 v[230:231], off
	s_waitcnt lgkmcnt(8)
	s_barrier
	s_waitcnt lgkmcnt(0)
	v_mfma_f32_16x16x32_bf16 v[126:129], v[130:133], v[172:175], v[126:129]
	v_mfma_f32_16x16x32_bf16 v[122:125], v[138:141], v[172:175], v[122:125]
	v_mfma_f32_16x16x32_bf16 v[114:117], v[130:133], v[206:209], v[114:117]
	v_mfma_f32_16x16x32_bf16 v[106:109], v[138:141], v[206:209], v[106:109]
	v_mfma_f32_16x16x32_bf16 v[98:101], v[130:133], v[214:217], v[98:101]
	v_mfma_f32_16x16x32_bf16 v[90:93], v[138:141], v[214:217], v[90:93]
	v_mfma_f32_16x16x32_bf16 v[82:85], v[130:133], v[222:225], v[82:85]
	v_mfma_f32_16x16x32_bf16 v[74:77], v[138:141], v[222:225], v[74:77]
	v_mfma_f32_16x16x32_bf16 v[126:129], v[134:137], v[182:185], v[126:129]
	v_mfma_f32_16x16x32_bf16 v[122:125], v[142:145], v[182:185], v[122:125]
	v_mfma_f32_16x16x32_bf16 v[114:117], v[134:137], v[210:213], v[114:117]
	v_mfma_f32_16x16x32_bf16 v[106:109], v[142:145], v[210:213], v[106:109]
	v_mfma_f32_16x16x32_bf16 v[98:101], v[134:137], v[218:221], v[98:101]
	v_mfma_f32_16x16x32_bf16 v[90:93], v[142:145], v[218:221], v[90:93]
	v_mfma_f32_16x16x32_bf16 v[82:85], v[134:137], v[226:229], v[82:85]
	v_mfma_f32_16x16x32_bf16 v[74:77], v[142:145], v[226:229], v[74:77]
	s_barrier
	s_add_i32 s48, 0, 0x1c000
	s_add_i32 s49, s65, s27
	v_add_u32_e32 v181, s48, v178
	v_lshl_add_u64 v[186:187], v[186:187], 0, s[94:95]
	s_mov_b32 m0, s49
	ds_read_b128 v[230:233], v181
	ds_read_b128 v[234:237], v181 offset:1024
	ds_read_b128 v[238:241], v181 offset:2048
	ds_read_b128 v[242:245], v181 offset:3072
	global_load_lds_dwordx4 v[186:187], off
	v_lshl_add_u64 v[186:187], v[246:247], 0, s[94:95]
	s_add_i32 m0, s49, 0x2000
	s_nop 0
	global_load_lds_dwordx4 v[186:187], off
	s_barrier
	s_waitcnt lgkmcnt(0)
	v_mfma_f32_16x16x32_bf16 v[118:121], v[230:233], v[172:175], v[118:121]
	v_mfma_f32_16x16x32_bf16 v[110:113], v[238:241], v[172:175], v[110:113]
	v_mfma_f32_16x16x32_bf16 v[102:105], v[230:233], v[206:209], v[102:105]
	v_mfma_f32_16x16x32_bf16 v[94:97], v[238:241], v[206:209], v[94:97]
	v_mfma_f32_16x16x32_bf16 v[86:89], v[230:233], v[214:217], v[86:89]
	v_mfma_f32_16x16x32_bf16 v[78:81], v[238:241], v[214:217], v[78:81]
	v_mfma_f32_16x16x32_bf16 v[70:73], v[230:233], v[222:225], v[70:73]
	v_mfma_f32_16x16x32_bf16 v[66:69], v[238:241], v[222:225], v[66:69]
	v_mfma_f32_16x16x32_bf16 v[118:121], v[234:237], v[182:185], v[118:121]
	v_mfma_f32_16x16x32_bf16 v[110:113], v[242:245], v[182:185], v[110:113]
	v_mfma_f32_16x16x32_bf16 v[102:105], v[234:237], v[210:213], v[102:105]
	v_mfma_f32_16x16x32_bf16 v[94:97], v[242:245], v[210:213], v[94:97]
	v_mfma_f32_16x16x32_bf16 v[86:89], v[234:237], v[218:221], v[86:89]
	v_mfma_f32_16x16x32_bf16 v[78:81], v[242:245], v[218:221], v[78:81]
	v_mfma_f32_16x16x32_bf16 v[70:73], v[234:237], v[226:229], v[70:73]
	v_mfma_f32_16x16x32_bf16 v[66:69], v[242:245], v[226:229], v[66:69]
	s_barrier
	s_mov_b32 m0, s55
	v_lshl_add_u64 v[186:187], v[248:249], 0, s[94:95]
	ds_read_b128 v[172:175], v180 offset:49152
	ds_read_b128 v[182:185], v180 offset:50176
	ds_read_b128 v[206:209], v180 offset:51200
	ds_read_b128 v[210:213], v180 offset:52224
	ds_read_b128 v[214:217], v180 offset:53248
	ds_read_b128 v[218:221], v180 offset:54272
	ds_read_b128 v[222:225], v180 offset:55296
	ds_read_b128 v[226:229], v180 offset:56320
	global_load_lds_dwordx4 v[186:187], off
	v_lshl_add_u64 v[186:187], v[250:251], 0, s[94:95]
	s_mov_b32 m0, s56
	s_nop 0
	global_load_lds_dwordx4 v[186:187], off
	s_barrier
	s_waitcnt lgkmcnt(0)
	v_mfma_f32_16x16x32_bf16 v[62:65], v[130:133], v[172:175], v[62:65]
	v_mfma_f32_16x16x32_bf16 v[58:61], v[138:141], v[172:175], v[58:61]
	v_mfma_f32_16x16x32_bf16 v[50:53], v[130:133], v[206:209], v[50:53]
	v_mfma_f32_16x16x32_bf16 v[42:45], v[138:141], v[206:209], v[42:45]
	v_mfma_f32_16x16x32_bf16 v[34:37], v[130:133], v[214:217], v[34:37]
	v_mfma_f32_16x16x32_bf16 v[26:29], v[138:141], v[214:217], v[26:29]
	v_mfma_f32_16x16x32_bf16 v[18:21], v[130:133], v[222:225], v[18:21]
	v_mfma_f32_16x16x32_bf16 v[10:13], v[138:141], v[222:225], v[10:13]
	v_mfma_f32_16x16x32_bf16 v[62:65], v[134:137], v[182:185], v[62:65]
	v_mfma_f32_16x16x32_bf16 v[58:61], v[142:145], v[182:185], v[58:61]
	v_mfma_f32_16x16x32_bf16 v[50:53], v[134:137], v[210:213], v[50:53]
	v_mfma_f32_16x16x32_bf16 v[42:45], v[142:145], v[210:213], v[42:45]
	v_mfma_f32_16x16x32_bf16 v[34:37], v[134:137], v[218:221], v[34:37]
	v_mfma_f32_16x16x32_bf16 v[26:29], v[142:145], v[218:221], v[26:29]
	v_mfma_f32_16x16x32_bf16 v[18:21], v[134:137], v[226:229], v[18:21]
	v_mfma_f32_16x16x32_bf16 v[10:13], v[142:145], v[226:229], v[10:13]
	s_barrier
	s_add_u32 s22, s22, 0x40080
	s_addc_u32 s23, s23, 0
	s_add_i32 s48, s48, s27
	v_lshl_add_u64 v[130:131], s[22:23], 0, v[0:1]
	s_mov_b32 m0, s48
	s_nop 0
	global_load_lds_dwordx4 v[130:131], off
	v_lshl_add_u64 v[130:131], s[22:23], 0, v[166:167]
	s_add_i32 m0, s48, 0x2000
	s_nop 0
	global_load_lds_dwordx4 v[130:131], off
	s_waitcnt vmcnt(6)
	s_barrier
	v_mfma_f32_16x16x32_bf16 v[54:57], v[230:233], v[172:175], v[54:57]
	v_mfma_f32_16x16x32_bf16 v[46:49], v[238:241], v[172:175], v[46:49]
	v_mfma_f32_16x16x32_bf16 v[38:41], v[230:233], v[206:209], v[38:41]
	v_mfma_f32_16x16x32_bf16 v[30:33], v[238:241], v[206:209], v[30:33]
	v_mfma_f32_16x16x32_bf16 v[22:25], v[230:233], v[214:217], v[22:25]
	v_mfma_f32_16x16x32_bf16 v[14:17], v[238:241], v[214:217], v[14:17]
	v_mfma_f32_16x16x32_bf16 v[6:9], v[230:233], v[222:225], v[6:9]
	v_mfma_f32_16x16x32_bf16 v[2:5], v[238:241], v[222:225], v[2:5]
	v_mfma_f32_16x16x32_bf16 v[54:57], v[234:237], v[182:185], v[54:57]
	v_mfma_f32_16x16x32_bf16 v[46:49], v[242:245], v[182:185], v[46:49]
	v_mfma_f32_16x16x32_bf16 v[38:41], v[234:237], v[210:213], v[38:41]
	v_mfma_f32_16x16x32_bf16 v[30:33], v[242:245], v[210:213], v[30:33]
	v_mfma_f32_16x16x32_bf16 v[22:25], v[234:237], v[218:221], v[22:25]
	v_mfma_f32_16x16x32_bf16 v[14:17], v[242:245], v[218:221], v[14:17]
	v_mfma_f32_16x16x32_bf16 v[6:9], v[234:237], v[226:229], v[6:9]
	v_mfma_f32_16x16x32_bf16 v[2:5], v[242:245], v[226:229], v[2:5]
	s_barrier
	s_add_i32 s64, s64, 2
	s_add_u32 s0, s0, 0x100
	s_addc_u32 s1, s1, 0
	s_add_u32 s62, s62, 0x100
	s_addc_u32 s63, s63, 0
	s_cmp_gt_u32 s64, 13
	s_cbranch_scc0 .LBB0_57
	v_lshl_or_b32 v172, s59, 8, v179
	v_ashrrev_i32_e32 v173, 31, v172
	v_cndmask_b32_e64 v131, 0, 1, s[2:3]
	v_lshl_add_u64 v[174:175], v[172:173], 2, s[8:9]
	v_mov_b32_e32 v130, 0
	v_cmp_ne_u32_e64 s[0:1], 1, v131
	s_andn2_b64 vcc, exec, s[2:3]
	v_mov_b32_e32 v134, 0
	v_mov_b32_e32 v135, 0
	v_mov_b32_e32 v136, 0
	v_mov_b32_e32 v137, 0
	s_cbranch_vccnz .LBB0_60
	global_load_dwordx4 v[134:137], v[174:175], off

.Lkprio_4:
.LBB0_95:
	s_add_u32 s22, s8, 0xfffc0080
	s_addc_u32 s23, s9, -1
	s_add_i32 s63, 0, 0x10000
	v_add_u32_e32 v78, s63, v178
	ds_read_b128 v[58:61], v78
	ds_read_b128 v[66:69], v78 offset:1024
	ds_read_b128 v[74:77], v78 offset:2048
	ds_read_b128 v[78:81], v78 offset:3072
	s_cmp_eq_u32 s49, 12
	s_cselect_b32 s29, s25, s23
	s_cselect_b32 s28, s26, s22
	s_cselect_b32 s23, s27, s47
	s_cselect_b32 s22, s30, s31
	v_lshl_add_u64 v[186:187], s[8:9], 0, v[168:169]
	s_add_i32 m0, s3, 0xc000
	ds_read_b128 v[172:175], v180
	ds_read_b128 v[182:185], v180 offset:1024
	ds_read_b128 v[206:209], v180 offset:2048
	ds_read_b128 v[210:213], v180 offset:3072
	ds_read_b128 v[214:217], v180 offset:4096
	ds_read_b128 v[218:221], v180 offset:5120
	ds_read_b128 v[222:225], v180 offset:6144
	ds_read_b128 v[226:229], v180 offset:7168
	global_load_lds_dwordx4 v[186:187], off
	v_lshl_add_u64 v[186:187], s[8:9], 0, v[170:171]
	s_add_i32 m0, s3, 0xe000
	s_nop 0
	global_load_lds_dwordx4 v[186:187], off
	s_waitcnt lgkmcnt(8)
	s_barrier
	s_waitcnt lgkmcnt(0)
	v_mfma_f32_16x16x32_bf16 v[142:145], v[58:61], v[172:175], v[142:145]
	v_mfma_f32_16x16x32_bf16 v[138:141], v[74:77], v[172:175], v[138:141]
	v_mfma_f32_16x16x32_bf16 v[126:129], v[58:61], v[206:209], v[126:129]
	v_mfma_f32_16x16x32_bf16 v[118:121], v[74:77], v[206:209], v[118:121]
	v_mfma_f32_16x16x32_bf16 v[110:113], v[58:61], v[214:217], v[110:113]
	v_mfma_f32_16x16x32_bf16 v[102:105], v[74:77], v[214:217], v[102:105]
	v_mfma_f32_16x16x32_bf16 v[94:97], v[58:61], v[222:225], v[94:97]
	v_mfma_f32_16x16x32_bf16 v[86:89], v[74:77], v[222:225], v[86:89]
	v_mfma_f32_16x16x32_bf16 v[142:145], v[66:69], v[182:185], v[142:145]
	v_mfma_f32_16x16x32_bf16 v[138:141], v[78:81], v[182:185], v[138:141]
	v_mfma_f32_16x16x32_bf16 v[126:129], v[66:69], v[210:213], v[126:129]
	v_mfma_f32_16x16x32_bf16 v[118:121], v[78:81], v[210:213], v[118:121]
	v_mfma_f32_16x16x32_bf16 v[110:113], v[66:69], v[218:221], v[110:113]
	v_mfma_f32_16x16x32_bf16 v[102:105], v[78:81], v[218:221], v[102:105]
	v_mfma_f32_16x16x32_bf16 v[94:97], v[66:69], v[226:229], v[94:97]
	v_mfma_f32_16x16x32_bf16 v[86:89], v[78:81], v[226:229], v[86:89]
	s_barrier
	s_add_i32 s66, 0, 0x14000
	s_add_i32 s63, s63, s37
	v_add_u32_e32 v181, s66, v178
	v_lshl_add_u64 v[186:187], s[22:23], 0, v[0:1]
	s_mov_b32 m0, s63
	ds_read_b128 v[230:233], v181
	ds_read_b128 v[234:237], v181 offset:1024
	ds_read_b128 v[238:241], v181 offset:2048
	ds_read_b128 v[242:245], v181 offset:3072
	global_load_lds_dwordx4 v[186:187], off
	v_lshl_add_u64 v[246:247], s[22:23], 0, v[166:167]
	s_add_i32 m0, s63, 0x2000
	s_nop 0
	global_load_lds_dwordx4 v[246:247], off
	s_barrier
	s_waitcnt lgkmcnt(0)
	v_mfma_f32_16x16x32_bf16 v[134:137], v[230:233], v[172:175], v[134:137]
	v_mfma_f32_16x16x32_bf16 v[130:133], v[238:241], v[172:175], v[130:133]
	v_mfma_f32_16x16x32_bf16 v[122:125], v[230:233], v[206:209], v[122:125]
	v_mfma_f32_16x16x32_bf16 v[114:117], v[238:241], v[206:209], v[114:117]
	v_mfma_f32_16x16x32_bf16 v[106:109], v[230:233], v[214:217], v[106:109]
	v_mfma_f32_16x16x32_bf16 v[98:101], v[238:241], v[214:217], v[98:101]
	v_mfma_f32_16x16x32_bf16 v[90:93], v[230:233], v[222:225], v[90:93]
	v_mfma_f32_16x16x32_bf16 v[82:85], v[238:241], v[222:225], v[82:85]
	v_mfma_f32_16x16x32_bf16 v[134:137], v[234:237], v[182:185], v[134:137]
	v_mfma_f32_16x16x32_bf16 v[130:133], v[242:245], v[182:185], v[130:133]
	v_mfma_f32_16x16x32_bf16 v[122:125], v[234:237], v[210:213], v[122:125]
	v_mfma_f32_16x16x32_bf16 v[114:117], v[242:245], v[210:213], v[114:117]
	v_mfma_f32_16x16x32_bf16 v[106:109], v[234:237], v[218:221], v[106:109]
	v_mfma_f32_16x16x32_bf16 v[98:101], v[242:245], v[218:221], v[98:101]
	v_mfma_f32_16x16x32_bf16 v[90:93], v[234:237], v[226:229], v[90:93]
	v_mfma_f32_16x16x32_bf16 v[82:85], v[242:245], v[226:229], v[82:85]
	s_barrier
	s_mov_b32 m0, s3
	v_lshl_add_u64 v[248:249], s[28:29], 0, v[162:163]
	ds_read_b128 v[172:175], v180 offset:16384
	ds_read_b128 v[182:185], v180 offset:17408
	ds_read_b128 v[206:209], v180 offset:18432
	ds_read_b128 v[210:213], v180 offset:19456
	ds_read_b128 v[214:217], v180 offset:20480
	ds_read_b128 v[218:221], v180 offset:21504
	ds_read_b128 v[222:225], v180 offset:22528
	ds_read_b128 v[226:229], v180 offset:23552
	global_load_lds_dwordx4 v[248:249], off
	v_lshl_add_u64 v[250:251], s[28:29], 0, v[164:165]
	s_mov_b32 m0, s56
	s_nop 0
	global_load_lds_dwordx4 v[250:251], off
	s_barrier
	s_waitcnt lgkmcnt(0)
	v_mfma_f32_16x16x32_bf16 v[70:73], v[58:61], v[172:175], v[70:73]
	v_mfma_f32_16x16x32_bf16 v[54:57], v[74:77], v[172:175], v[54:57]
	v_mfma_f32_16x16x32_bf16 v[46:49], v[58:61], v[206:209], v[46:49]
	v_mfma_f32_16x16x32_bf16 v[38:41], v[74:77], v[206:209], v[38:41]
	v_mfma_f32_16x16x32_bf16 v[30:33], v[58:61], v[214:217], v[30:33]
	v_mfma_f32_16x16x32_bf16 v[22:25], v[74:77], v[214:217], v[22:25]
	v_mfma_f32_16x16x32_bf16 v[14:17], v[58:61], v[222:225], v[14:17]
	v_mfma_f32_16x16x32_bf16 v[6:9], v[74:77], v[222:225], v[6:9]
	v_mfma_f32_16x16x32_bf16 v[70:73], v[66:69], v[182:185], v[70:73]
	v_mfma_f32_16x16x32_bf16 v[54:57], v[78:81], v[182:185], v[54:57]
	v_mfma_f32_16x16x32_bf16 v[46:49], v[66:69], v[210:213], v[46:49]
	v_mfma_f32_16x16x32_bf16 v[38:41], v[78:81], v[210:213], v[38:41]
	v_mfma_f32_16x16x32_bf16 v[30:33], v[66:69], v[218:221], v[30:33]
	v_mfma_f32_16x16x32_bf16 v[22:25], v[78:81], v[218:221], v[22:25]
	v_mfma_f32_16x16x32_bf16 v[14:17], v[66:69], v[226:229], v[14:17]
	v_mfma_f32_16x16x32_bf16 v[6:9], v[78:81], v[226:229], v[6:9]
	s_barrier
	s_add_u32 s64, s22, 0x40000
	s_addc_u32 s65, s23, 0
	s_add_i32 s63, s66, s37
	v_lshl_add_u64 v[58:59], s[64:65], 0, v[0:1]
	s_mov_b32 m0, s63
	s_nop 0
	global_load_lds_dwordx4 v[58:59], off
	v_lshl_add_u64 v[58:59], s[64:65], 0, v[166:167]
	s_add_i32 m0, s63, 0x2000
	s_nop 0
	global_load_lds_dwordx4 v[58:59], off
	s_waitcnt vmcnt(6)
	s_barrier
	v_mfma_f32_16x16x32_bf16 v[50:53], v[238:241], v[172:175], v[50:53]
	v_mfma_f32_16x16x32_bf16 v[42:45], v[230:233], v[206:209], v[42:45]
	v_mfma_f32_16x16x32_bf16 v[34:37], v[238:241], v[206:209], v[34:37]
	v_mfma_f32_16x16x32_bf16 v[26:29], v[230:233], v[214:217], v[26:29]
	v_mfma_f32_16x16x32_bf16 v[18:21], v[238:241], v[214:217], v[18:21]
	v_mfma_f32_16x16x32_bf16 v[10:13], v[230:233], v[222:225], v[10:13]
	v_mfma_f32_16x16x32_bf16 v[2:5], v[238:241], v[222:225], v[2:5]
	v_mfma_f32_16x16x32_bf16 v[58:61], v[230:233], v[172:175], v[62:65]
	v_mfma_f32_16x16x32_bf16 v[50:53], v[242:245], v[182:185], v[50:53]
	v_mfma_f32_16x16x32_bf16 v[42:45], v[234:237], v[210:213], v[42:45]
	v_mfma_f32_16x16x32_bf16 v[34:37], v[242:245], v[210:213], v[34:37]
	v_mfma_f32_16x16x32_bf16 v[26:29], v[234:237], v[218:221], v[26:29]
	v_mfma_f32_16x16x32_bf16 v[18:21], v[242:245], v[218:221], v[18:21]
	v_mfma_f32_16x16x32_bf16 v[10:13], v[234:237], v[226:229], v[10:13]
	v_mfma_f32_16x16x32_bf16 v[2:5], v[242:245], v[226:229], v[2:5]
	v_mfma_f32_16x16x32_bf16 v[58:61], v[234:237], v[182:185], v[58:61]
	s_barrier
	s_add_i32 s63, 0, 0x18000
	v_add_u32_e32 v78, s63, v178
	ds_read_b128 v[62:65], v78
	ds_read_b128 v[66:69], v78 offset:1024
	ds_read_b128 v[74:77], v78 offset:2048
	ds_read_b128 v[78:81], v78 offset:3072
	s_add_u32 s28, s28, 0x40000
	s_addc_u32 s29, s29, 0
	s_mov_b32 m0, s57
	v_lshl_add_u64 v[230:231], s[28:29], 0, v[162:163]
	ds_read_b128 v[172:175], v180 offset:32768
	ds_read_b128 v[182:185], v180 offset:33792
	ds_read_b128 v[206:209], v180 offset:34816
	ds_read_b128 v[210:213], v180 offset:35840
	ds_read_b128 v[214:217], v180 offset:36864
	ds_read_b128 v[218:221], v180 offset:37888
	ds_read_b128 v[222:225], v180 offset:38912
	ds_read_b128 v[226:229], v180 offset:39936
	global_load_lds_dwordx4 v[230:231], off
	v_lshl_add_u64 v[230:231], s[28:29], 0, v[164:165]
	s_mov_b32 m0, s58
	s_nop 0
	global_load_lds_dwordx4 v[230:231], off
	s_waitcnt lgkmcnt(8)
	s_barrier
	s_waitcnt lgkmcnt(0)
	v_mfma_f32_16x16x32_bf16 v[142:145], v[62:65], v[172:175], v[142:145]
	v_mfma_f32_16x16x32_bf16 v[138:141], v[74:77], v[172:175], v[138:141]
	v_mfma_f32_16x16x32_bf16 v[126:129], v[62:65], v[206:209], v[126:129]
	v_mfma_f32_16x16x32_bf16 v[118:121], v[74:77], v[206:209], v[118:121]
	v_mfma_f32_16x16x32_bf16 v[110:113], v[62:65], v[214:217], v[110:113]
	v_mfma_f32_16x16x32_bf16 v[102:105], v[74:77], v[214:217], v[102:105]
	v_mfma_f32_16x16x32_bf16 v[94:97], v[62:65], v[222:225], v[94:97]
	v_mfma_f32_16x16x32_bf16 v[86:89], v[74:77], v[222:225], v[86:89]
	v_mfma_f32_16x16x32_bf16 v[142:145], v[66:69], v[182:185], v[142:145]
	v_mfma_f32_16x16x32_bf16 v[138:141], v[78:81], v[182:185], v[138:141]
	v_mfma_f32_16x16x32_bf16 v[126:129], v[66:69], v[210:213], v[126:129]
	v_mfma_f32_16x16x32_bf16 v[118:121], v[78:81], v[210:213], v[118:121]
	v_mfma_f32_16x16x32_bf16 v[110:113], v[66:69], v[218:221], v[110:113]
	v_mfma_f32_16x16x32_bf16 v[102:105], v[78:81], v[218:221], v[102:105]
	v_mfma_f32_16x16x32_bf16 v[94:97], v[66:69], v[226:229], v[94:97]
	v_mfma_f32_16x16x32_bf16 v[86:89], v[78:81], v[226:229], v[86:89]
	s_barrier
	s_add_i32 s28, 0, 0x1c000
	s_add_i32 s29, s63, s37
	v_add_u32_e32 v181, s28, v178
	v_lshl_add_u64 v[186:187], v[186:187], 0, s[94:95]
	s_mov_b32 m0, s29
	ds_read_b128 v[230:233], v181
	ds_read_b128 v[234:237], v181 offset:1024
	ds_read_b128 v[238:241], v181 offset:2048
	ds_read_b128 v[242:245], v181 offset:3072
	global_load_lds_dwordx4 v[186:187], off
	v_lshl_add_u64 v[186:187], v[246:247], 0, s[94:95]
	s_add_i32 m0, s29, 0x2000
	s_nop 0
	global_load_lds_dwordx4 v[186:187], off
	s_barrier
	s_waitcnt lgkmcnt(0)
	v_mfma_f32_16x16x32_bf16 v[134:137], v[230:233], v[172:175], v[134:137]
	v_mfma_f32_16x16x32_bf16 v[130:133], v[238:241], v[172:175], v[130:133]
	v_mfma_f32_16x16x32_bf16 v[122:125], v[230:233], v[206:209], v[122:125]
	v_mfma_f32_16x16x32_bf16 v[114:117], v[238:241], v[206:209], v[114:117]
	v_mfma_f32_16x16x32_bf16 v[106:109], v[230:233], v[214:217], v[106:109]
	v_mfma_f32_16x16x32_bf16 v[98:101], v[238:241], v[214:217], v[98:101]
	v_mfma_f32_16x16x32_bf16 v[90:93], v[230:233], v[222:225], v[90:93]
	v_mfma_f32_16x16x32_bf16 v[82:85], v[238:241], v[222:225], v[82:85]
	v_mfma_f32_16x16x32_bf16 v[134:137], v[234:237], v[182:185], v[134:137]
	v_mfma_f32_16x16x32_bf16 v[130:133], v[242:245], v[182:185], v[130:133]
	v_mfma_f32_16x16x32_bf16 v[122:125], v[234:237], v[210:213], v[122:125]
	v_mfma_f32_16x16x32_bf16 v[114:117], v[242:245], v[210:213], v[114:117]
	v_mfma_f32_16x16x32_bf16 v[106:109], v[234:237], v[218:221], v[106:109]
	v_mfma_f32_16x16x32_bf16 v[98:101], v[242:245], v[218:221], v[98:101]
	v_mfma_f32_16x16x32_bf16 v[90:93], v[234:237], v[226:229], v[90:93]
	v_mfma_f32_16x16x32_bf16 v[82:85], v[242:245], v[226:229], v[82:85]
	s_barrier
	s_mov_b32 m0, s59
	v_lshl_add_u64 v[186:187], v[248:249], 0, s[94:95]
	ds_read_b128 v[172:175], v180 offset:49152
	ds_read_b128 v[182:185], v180 offset:50176
	ds_read_b128 v[206:209], v180 offset:51200
	ds_read_b128 v[210:213], v180 offset:52224
	ds_read_b128 v[214:217], v180 offset:53248
	ds_read_b128 v[218:221], v180 offset:54272
	ds_read_b128 v[222:225], v180 offset:55296
	ds_read_b128 v[226:229], v180 offset:56320
	global_load_lds_dwordx4 v[186:187], off
	v_lshl_add_u64 v[186:187], v[250:251], 0, s[94:95]
	s_mov_b32 m0, s60
	s_nop 0
	global_load_lds_dwordx4 v[186:187], off
	s_barrier
	s_waitcnt lgkmcnt(0)
	v_mfma_f32_16x16x32_bf16 v[70:73], v[62:65], v[172:175], v[70:73]
	v_mfma_f32_16x16x32_bf16 v[54:57], v[74:77], v[172:175], v[54:57]
	v_mfma_f32_16x16x32_bf16 v[46:49], v[62:65], v[206:209], v[46:49]
	v_mfma_f32_16x16x32_bf16 v[38:41], v[74:77], v[206:209], v[38:41]
	v_mfma_f32_16x16x32_bf16 v[30:33], v[62:65], v[214:217], v[30:33]
	v_mfma_f32_16x16x32_bf16 v[22:25], v[74:77], v[214:217], v[22:25]
	v_mfma_f32_16x16x32_bf16 v[14:17], v[62:65], v[222:225], v[14:17]
	v_mfma_f32_16x16x32_bf16 v[6:9], v[74:77], v[222:225], v[6:9]
	v_mfma_f32_16x16x32_bf16 v[70:73], v[66:69], v[182:185], v[70:73]
	v_mfma_f32_16x16x32_bf16 v[54:57], v[78:81], v[182:185], v[54:57]
	v_mfma_f32_16x16x32_bf16 v[46:49], v[66:69], v[210:213], v[46:49]
	v_mfma_f32_16x16x32_bf16 v[38:41], v[78:81], v[210:213], v[38:41]
	v_mfma_f32_16x16x32_bf16 v[30:33], v[66:69], v[218:221], v[30:33]
	v_mfma_f32_16x16x32_bf16 v[22:25], v[78:81], v[218:221], v[22:25]
	v_mfma_f32_16x16x32_bf16 v[14:17], v[66:69], v[226:229], v[14:17]
	v_mfma_f32_16x16x32_bf16 v[6:9], v[78:81], v[226:229], v[6:9]
	s_barrier
	s_add_u32 s22, s22, 0x40080
	s_addc_u32 s23, s23, 0
	s_add_i32 s28, s28, s37
	v_lshl_add_u64 v[62:63], s[22:23], 0, v[0:1]
	s_mov_b32 m0, s28
	s_nop 0
	global_load_lds_dwordx4 v[62:63], off
	v_lshl_add_u64 v[62:63], s[22:23], 0, v[166:167]
	s_add_i32 m0, s28, 0x2000
	s_nop 0
	global_load_lds_dwordx4 v[62:63], off
	s_waitcnt vmcnt(6)
	s_barrier
	v_mfma_f32_16x16x32_bf16 v[58:61], v[230:233], v[172:175], v[58:61]
	v_mfma_f32_16x16x32_bf16 v[50:53], v[238:241], v[172:175], v[50:53]
	v_mfma_f32_16x16x32_bf16 v[42:45], v[230:233], v[206:209], v[42:45]
	v_mfma_f32_16x16x32_bf16 v[34:37], v[238:241], v[206:209], v[34:37]
	v_mfma_f32_16x16x32_bf16 v[26:29], v[230:233], v[214:217], v[26:29]
	v_mfma_f32_16x16x32_bf16 v[18:21], v[238:241], v[214:217], v[18:21]
	v_mfma_f32_16x16x32_bf16 v[10:13], v[230:233], v[222:225], v[10:13]
	v_mfma_f32_16x16x32_bf16 v[2:5], v[238:241], v[222:225], v[2:5]
	v_mfma_f32_16x16x32_bf16 v[62:65], v[234:237], v[182:185], v[58:61]
	v_mfma_f32_16x16x32_bf16 v[50:53], v[242:245], v[182:185], v[50:53]
	v_mfma_f32_16x16x32_bf16 v[42:45], v[234:237], v[210:213], v[42:45]
	v_mfma_f32_16x16x32_bf16 v[34:37], v[242:245], v[210:213], v[34:37]
	v_mfma_f32_16x16x32_bf16 v[26:29], v[234:237], v[218:221], v[26:29]
	v_mfma_f32_16x16x32_bf16 v[18:21], v[242:245], v[218:221], v[18:21]
	v_mfma_f32_16x16x32_bf16 v[10:13], v[234:237], v[226:229], v[10:13]
	v_mfma_f32_16x16x32_bf16 v[2:5], v[242:245], v[226:229], v[2:5]
	s_barrier
	s_add_i32 s49, s49, 2
	s_add_u32 s8, s8, 0x100
	s_addc_u32 s9, s9, 0
	s_add_u32 s31, s31, 0x100
	s_addc_u32 s47, s47, 0
	s_cmp_gt_u32 s49, 13
	s_cbranch_scc0 .LBB0_95
	v_lshl_or_b32 v172, s24, 7, v179
	v_ashrrev_i32_e32 v173, 31, v172
	v_lshlrev_b64 v[58:59], 2, v[172:173]
	v_lshl_add_u64 v[60:61], s[40:41], 0, v[58:59]
	v_lshl_add_u64 v[74:75], s[44:45], 0, v[58:59]
	global_load_dwordx4 v[66:69], v[60:61], off offset:16
	global_load_dwordx4 v[78:81], v[60:61], off
	s_nop 0
	global_load_dwordx4 v[58:61], v[74:75], off offset:16
	s_nop 0
	global_load_dwordx4 v[74:77], v[74:75], off
	v_lshl_add_u32 v174, s2, 8, v177
	v_ashrrev_i32_e32 v175, 31, v174
	v_lshl_add_u64 v[172:173], v[172:173], 1, s[20:21]
	v_lshlrev_b64 v[182:183], 11, v[174:175]
	s_mov_b32 s2, 0x50000
	s_mov_b32 s24, s46
	s_mov_b64 s[22:23], s[54:55]
	s_mov_b64 s[8:9], s[50:51]
	s_waitcnt vmcnt(0)
	v_add_f32_e32 v138, v138, v66
	v_add_f32_e32 v126, v126, v78
	v_add_f32_e32 v130, v130, v58
	v_mul_f32_e32 v130, 0xbfb8aa3b, v130
	v_add_f32_e32 v131, v131, v59
	v_add_f32_e32 v122, v122, v74
	v_exp_f32_e32 v130, v130
	v_mul_f32_e32 v131, 0xbfb8aa3b, v131
	v_mul_f32_e32 v122, 0xbfb8aa3b, v122
	v_add_f32_e32 v123, v123, v75
	v_exp_f32_e32 v131, v131
	v_exp_f32_e32 v122, v122
	v_mul_f32_e32 v123, 0xbfb8aa3b, v123
	v_add_f32_e32 v124, v124, v76
	v_exp_f32_e32 v123, v123
	v_mul_f32_e32 v124, 0xbfb8aa3b, v124
	v_add_f32_e32 v125, v125, v77
	v_add_f32_e32 v114, v114, v58
	v_exp_f32_e32 v124, v124
	v_mul_f32_e32 v125, 0xbfb8aa3b, v125
	v_mul_f32_e32 v114, 0xbfb8aa3b, v114
	v_add_f32_e32 v115, v115, v59
	v_add_f32_e32 v106, v106, v74
	v_add_f32_e32 v130, 1.0, v130
	v_exp_f32_e32 v125, v125
	v_exp_f32_e32 v114, v114
	v_mul_f32_e32 v115, 0xbfb8aa3b, v115
	v_mul_f32_e32 v106, 0xbfb8aa3b, v106
	v_add_f32_e32 v107, v107, v75
	v_rcp_f32_e32 v130, v130
	v_add_f32_e32 v131, 1.0, v131
	v_add_f32_e32 v122, 1.0, v122
	v_exp_f32_e32 v115, v115
	v_exp_f32_e32 v106, v106
	v_mul_f32_e32 v107, 0xbfb8aa3b, v107
	v_add_f32_e32 v108, v108, v76
	v_rcp_f32_e32 v131, v131
	v_rcp_f32_e32 v122, v122
	v_add_f32_e32 v123, 1.0, v123
	v_exp_f32_e32 v107, v107
	v_mul_f32_e32 v108, 0xbfb8aa3b, v108
	v_add_f32_e32 v109, v109, v77
	v_add_f32_e32 v98, v98, v58
	v_rcp_f32_e32 v123, v123
	v_add_f32_e32 v124, 1.0, v124
	v_exp_f32_e32 v108, v108
	v_mul_f32_e32 v109, 0xbfb8aa3b, v109
	v_mul_f32_e32 v98, 0xbfb8aa3b, v98
	v_add_f32_e32 v99, v99, v59
	v_add_f32_e32 v90, v90, v74
	v_rcp_f32_e32 v124, v124
	v_add_f32_e32 v125, 1.0, v125
	v_add_f32_e32 v114, 1.0, v114
	v_exp_f32_e32 v109, v109
	v_exp_f32_e32 v98, v98
	v_mul_f32_e32 v99, 0xbfb8aa3b, v99
	v_mul_f32_e32 v90, 0xbfb8aa3b, v90
	v_add_f32_e32 v91, v91, v75
	v_mul_f32_e32 v138, v138, v130
	v_add_f32_e32 v130, v139, v67
	v_rcp_f32_e32 v125, v125
	v_rcp_f32_e32 v114, v114
	v_add_f32_e32 v115, 1.0, v115
	v_add_f32_e32 v106, 1.0, v106
	v_exp_f32_e32 v99, v99
	v_exp_f32_e32 v90, v90
	v_mul_f32_e32 v91, 0xbfb8aa3b, v91
	v_add_f32_e32 v92, v92, v76
	v_mul_f32_e32 v139, v130, v131
	v_add_f32_e32 v131, v132, v60
	v_mul_f32_e32 v122, v126, v122
	v_add_f32_e32 v126, v127, v79
	v_rcp_f32_e32 v115, v115
	v_rcp_f32_e32 v106, v106
	v_add_f32_e32 v107, 1.0, v107
	v_exp_f32_e32 v91, v91
	v_mul_f32_e32 v92, 0xbfb8aa3b, v92
	v_add_f32_e32 v93, v93, v77
	v_add_f32_e32 v82, v82, v58
	v_mul_f32_e32 v131, 0xbfb8aa3b, v131
	v_mul_f32_e32 v123, v126, v123
	v_add_f32_e32 v126, v128, v80
	v_rcp_f32_e32 v107, v107
	v_add_f32_e32 v108, 1.0, v108
	v_exp_f32_e32 v92, v92
	v_mul_f32_e32 v93, 0xbfb8aa3b, v93
	v_mul_f32_e32 v82, 0xbfb8aa3b, v82
	v_add_f32_e32 v83, v83, v59
	v_add_f32_e32 v50, v50, v58
	v_exp_f32_e32 v131, v131
	v_mul_f32_e32 v124, v126, v124
	v_add_f32_e32 v126, v129, v81
	v_add_f32_e32 v118, v118, v66
	v_rcp_f32_e32 v108, v108
	v_add_f32_e32 v109, 1.0, v109
	v_add_f32_e32 v98, 1.0, v98
	v_exp_f32_e32 v93, v93
	v_exp_f32_e32 v82, v82
	v_mul_f32_e32 v83, 0xbfb8aa3b, v83
	v_mul_f32_e32 v50, 0xbfb8aa3b, v50
	v_add_f32_e32 v51, v51, v59
	v_mul_f32_e32 v125, v126, v125
	v_mul_f32_e32 v126, v118, v114
	v_add_f32_e32 v114, v119, v67
	v_add_f32_e32 v110, v110, v78
	v_rcp_f32_e32 v109, v109
	v_rcp_f32_e32 v98, v98
	v_add_f32_e32 v99, 1.0, v99
	v_add_f32_e32 v90, 1.0, v90
	v_exp_f32_e32 v83, v83
	v_exp_f32_e32 v50, v50
	v_mul_f32_e32 v51, 0xbfb8aa3b, v51
	v_add_f32_e32 v34, v34, v58
	v_mul_f32_e32 v127, v114, v115
	v_add_f32_e32 v115, v116, v60
	v_mul_f32_e32 v106, v110, v106
	v_add_f32_e32 v110, v111, v79
	v_rcp_f32_e32 v99, v99
	v_rcp_f32_e32 v90, v90
	v_add_f32_e32 v91, 1.0, v91
	v_exp_f32_e32 v51, v51
	v_mul_f32_e32 v34, 0xbfb8aa3b, v34
	v_add_f32_e32 v35, v35, v59
	v_mul_f32_e32 v115, 0xbfb8aa3b, v115
	v_mul_f32_e32 v107, v110, v107
	v_add_f32_e32 v110, v112, v80
	v_rcp_f32_e32 v91, v91
	v_add_f32_e32 v92, 1.0, v92
	v_exp_f32_e32 v34, v34
	v_mul_f32_e32 v35, 0xbfb8aa3b, v35
	v_add_f32_e32 v18, v18, v58
	v_add_f32_e32 v131, 1.0, v131
	v_exp_f32_e32 v115, v115
	v_mul_f32_e32 v108, v110, v108
	v_add_f32_e32 v110, v113, v81
	v_add_f32_e32 v102, v102, v66
	v_rcp_f32_e32 v92, v92
	v_add_f32_e32 v93, 1.0, v93
	v_add_f32_e32 v82, 1.0, v82
	v_exp_f32_e32 v35, v35
	v_mul_f32_e32 v18, 0xbfb8aa3b, v18
	v_add_f32_e32 v19, v19, v59
	v_rcp_f32_e32 v131, v131
	v_mul_f32_e32 v109, v110, v109
	v_mul_f32_e32 v110, v102, v98
	v_add_f32_e32 v98, v103, v67
	v_add_f32_e32 v94, v94, v78
	v_rcp_f32_e32 v93, v93
	v_rcp_f32_e32 v82, v82
	v_add_f32_e32 v83, 1.0, v83
	v_add_f32_e32 v50, 1.0, v50
	v_exp_f32_e32 v18, v18
	v_mul_f32_e32 v19, 0xbfb8aa3b, v19
	v_add_f32_e32 v2, v2, v58
	v_mul_f32_e32 v111, v98, v99
	v_add_f32_e32 v99, v100, v60
	v_mul_f32_e32 v90, v94, v90
	v_add_f32_e32 v94, v95, v79
	v_rcp_f32_e32 v83, v83
	v_rcp_f32_e32 v50, v50
	v_add_f32_e32 v51, 1.0, v51
	v_exp_f32_e32 v19, v19
	v_mul_f32_e32 v2, 0xbfb8aa3b, v2
	v_add_f32_e32 v3, v3, v59
	v_add_f32_e32 v134, v134, v74
	v_mul_f32_e32 v99, 0xbfb8aa3b, v99
	v_mul_f32_e32 v91, v94, v91
	v_add_f32_e32 v94, v96, v80
	v_rcp_f32_e32 v51, v51
	v_add_f32_e32 v34, 1.0, v34
	v_exp_f32_e32 v2, v2
	v_mul_f32_e32 v3, 0xbfb8aa3b, v3
	v_mul_f32_e32 v134, 0xbfb8aa3b, v134
	v_add_f32_e32 v135, v135, v75
	v_add_f32_e32 v130, v140, v68
	v_add_f32_e32 v115, 1.0, v115
	v_exp_f32_e32 v99, v99
	v_mul_f32_e32 v92, v94, v92
	v_add_f32_e32 v94, v97, v81
	v_add_f32_e32 v86, v86, v66
	v_rcp_f32_e32 v34, v34
	v_add_f32_e32 v35, 1.0, v35
	v_exp_f32_e32 v3, v3
	v_exp_f32_e32 v134, v134
	v_mul_f32_e32 v135, 0xbfb8aa3b, v135
	v_add_f32_e32 v136, v136, v76
	v_mul_f32_e32 v140, v130, v131
	v_add_f32_e32 v131, v133, v61
	v_rcp_f32_e32 v115, v115
	v_mul_f32_e32 v93, v94, v93
	v_mul_f32_e32 v94, v86, v82
	v_add_f32_e32 v82, v87, v67
	v_add_f32_e32 v54, v54, v66
	v_rcp_f32_e32 v35, v35
	v_add_f32_e32 v18, 1.0, v18
	v_exp_f32_e32 v135, v135
	v_mul_f32_e32 v136, 0xbfb8aa3b, v136
	v_add_f32_e32 v137, v137, v77
	v_mul_f32_e32 v131, 0xbfb8aa3b, v131
	v_mul_f32_e32 v95, v82, v83
	v_add_f32_e32 v83, v84, v60
	v_mul_f32_e32 v54, v54, v50
	v_add_f32_e32 v50, v55, v67
	v_rcp_f32_e32 v18, v18
	v_add_f32_e32 v19, 1.0, v19
	v_exp_f32_e32 v136, v136
	v_mul_f32_e32 v137, 0xbfb8aa3b, v137
	v_exp_f32_e32 v131, v131
	v_mul_f32_e32 v83, 0xbfb8aa3b, v83
	v_mul_f32_e32 v55, v50, v51
	v_add_f32_e32 v51, v52, v60
	v_add_f32_e32 v38, v38, v66
	v_rcp_f32_e32 v19, v19
	v_add_f32_e32 v2, 1.0, v2
	v_exp_f32_e32 v137, v137
	v_add_f32_e32 v114, v120, v68
	v_add_f32_e32 v99, 1.0, v99
	v_exp_f32_e32 v83, v83
	v_mul_f32_e32 v51, 0xbfb8aa3b, v51
	v_mul_f32_e32 v38, v38, v34
	v_add_f32_e32 v34, v39, v67
	v_rcp_f32_e32 v2, v2
	v_add_f32_e32 v3, 1.0, v3
	v_add_f32_e32 v134, 1.0, v134
	v_mul_f32_e32 v120, v114, v115
	v_add_f32_e32 v115, v117, v61
	v_rcp_f32_e32 v99, v99
	v_exp_f32_e32 v51, v51
	v_mul_f32_e32 v39, v34, v35
	v_add_f32_e32 v35, v36, v60
	v_add_f32_e32 v22, v22, v66
	v_rcp_f32_e32 v3, v3
	v_rcp_f32_e32 v134, v134
	v_add_f32_e32 v135, 1.0, v135
	v_mul_f32_e32 v115, 0xbfb8aa3b, v115
	v_mul_f32_e32 v35, 0xbfb8aa3b, v35
	v_mul_f32_e32 v22, v22, v18
	v_add_f32_e32 v18, v23, v67
	v_rcp_f32_e32 v135, v135
	v_add_f32_e32 v136, 1.0, v136
	v_add_f32_e32 v131, 1.0, v131
	v_exp_f32_e32 v115, v115
	v_exp_f32_e32 v35, v35
	v_mul_f32_e32 v23, v18, v19
	v_add_f32_e32 v19, v20, v60
	v_add_f32_e32 v6, v6, v66
	v_rcp_f32_e32 v136, v136
	v_add_f32_e32 v137, 1.0, v137
	v_rcp_f32_e32 v131, v131
	v_add_f32_e32 v98, v104, v68
	v_add_f32_e32 v83, 1.0, v83
	v_mul_f32_e32 v19, 0xbfb8aa3b, v19
	v_mul_f32_e32 v6, v6, v2
	v_add_f32_e32 v2, v7, v67
	v_add_f32_e32 v142, v142, v78
	v_rcp_f32_e32 v137, v137
	v_mul_f32_e32 v104, v98, v99
	v_add_f32_e32 v99, v101, v61
	v_rcp_f32_e32 v83, v83
	v_add_f32_e32 v51, 1.0, v51
	v_exp_f32_e32 v19, v19
	v_mul_f32_e32 v7, v2, v3
	v_add_f32_e32 v3, v4, v60
	v_mul_f32_e32 v134, v142, v134
	v_add_f32_e32 v142, v143, v79
	v_mul_f32_e32 v99, 0xbfb8aa3b, v99
	v_rcp_f32_e32 v51, v51
	v_mul_f32_e32 v3, 0xbfb8aa3b, v3
	v_mul_f32_e32 v135, v142, v135
	v_add_f32_e32 v142, v144, v80
	v_add_f32_e32 v130, v141, v69
	v_add_f32_e32 v115, 1.0, v115
	v_exp_f32_e32 v99, v99
	v_add_f32_e32 v62, v62, v74
	v_add_f32_e32 v35, 1.0, v35
	v_exp_f32_e32 v3, v3
	v_mul_f32_e32 v136, v142, v136
	v_add_f32_e32 v142, v145, v81
	v_mul_f32_e32 v141, v130, v131
	v_lshl_add_u64 v[130:131], v[172:173], 0, v[182:183]
	v_cvt_pk_bf16_f32 v132, v134, v135
	v_rcp_f32_e32 v115, v115
	v_add_f32_e32 v82, v88, v68
	v_mul_f32_e32 v62, 0xbfb8aa3b, v62
	v_add_f32_e32 v63, v63, v75
	v_rcp_f32_e32 v35, v35
	v_mul_f32_e32 v137, v142, v137
	v_cvt_pk_bf16_f32 v133, v136, v137
	v_cvt_pk_bf16_f32 v134, v138, v139
	v_cvt_pk_bf16_f32 v135, v140, v141
	global_store_dwordx4 v[130:131], v[132:135], off
	v_mul_f32_e32 v88, v82, v83
	v_add_f32_e32 v83, v85, v61
	v_or_b32_e32 v132, 16, v174
	v_exp_f32_e32 v62, v62
	v_mul_f32_e32 v63, 0xbfb8aa3b, v63
	v_add_f32_e32 v64, v64, v76
	v_add_f32_e32 v50, v56, v68
	v_add_f32_e32 v42, v42, v74
	v_add_f32_e32 v19, 1.0, v19
	v_ashrrev_i32_e32 v133, 31, v132
	v_mul_f32_e32 v83, 0xbfb8aa3b, v83
	v_exp_f32_e32 v63, v63
	v_mul_f32_e32 v64, 0xbfb8aa3b, v64
	v_add_f32_e32 v65, v65, v77
	v_mul_f32_e32 v56, v50, v51
	v_add_f32_e32 v51, v53, v61
	v_mul_f32_e32 v42, 0xbfb8aa3b, v42
	v_add_f32_e32 v43, v43, v75
	v_rcp_f32_e32 v19, v19
	v_lshlrev_b64 v[132:133], 11, v[132:133]
	v_add_f32_e32 v114, v121, v69
	v_add_f32_e32 v99, 1.0, v99
	v_exp_f32_e32 v83, v83
	v_exp_f32_e32 v64, v64
	v_mul_f32_e32 v65, 0xbfb8aa3b, v65
	v_mul_f32_e32 v51, 0xbfb8aa3b, v51
	v_exp_f32_e32 v42, v42
	v_mul_f32_e32 v43, 0xbfb8aa3b, v43
	v_add_f32_e32 v44, v44, v76
	v_add_f32_e32 v34, v40, v68
	v_add_f32_e32 v26, v26, v74
	v_add_f32_e32 v3, 1.0, v3
	v_mul_f32_e32 v117, v114, v115
	v_lshl_add_u64 v[118:119], v[172:173], 0, v[132:133]
	v_cvt_pk_bf16_f32 v114, v122, v123
	v_rcp_f32_e32 v99, v99
	v_exp_f32_e32 v65, v65
	v_exp_f32_e32 v51, v51
	v_exp_f32_e32 v43, v43
	v_mul_f32_e32 v44, 0xbfb8aa3b, v44
	v_add_f32_e32 v45, v45, v77
	v_mul_f32_e32 v40, v34, v35
	v_add_f32_e32 v35, v37, v61
	v_mul_f32_e32 v26, 0xbfb8aa3b, v26
	v_add_f32_e32 v27, v27, v75
	v_rcp_f32_e32 v3, v3
	v_cvt_pk_bf16_f32 v115, v124, v125
	v_cvt_pk_bf16_f32 v116, v126, v127
	v_cvt_pk_bf16_f32 v117, v120, v117
	global_store_dwordx4 v[118:119], v[114:117], off
	v_add_f32_e32 v62, 1.0, v62
	v_exp_f32_e32 v44, v44
	v_or_b32_e32 v114, 32, v174
	v_mul_f32_e32 v45, 0xbfb8aa3b, v45
	v_mul_f32_e32 v35, 0xbfb8aa3b, v35
	v_exp_f32_e32 v26, v26
	v_mul_f32_e32 v27, 0xbfb8aa3b, v27
	v_add_f32_e32 v28, v28, v76
	v_add_f32_e32 v18, v24, v68
	v_add_f32_e32 v10, v10, v74
	v_ashrrev_i32_e32 v115, 31, v114
	v_rcp_f32_e32 v62, v62
	v_add_f32_e32 v63, 1.0, v63
	v_exp_f32_e32 v45, v45
	v_exp_f32_e32 v35, v35
	v_exp_f32_e32 v27, v27
	v_mul_f32_e32 v28, 0xbfb8aa3b, v28
	v_add_f32_e32 v29, v29, v77
	v_mul_f32_e32 v24, v18, v19
	v_add_f32_e32 v19, v21, v61
	v_mul_f32_e32 v10, 0xbfb8aa3b, v10
	v_add_f32_e32 v11, v11, v75
	v_lshlrev_b64 v[114:115], 11, v[114:115]
	v_add_f32_e32 v98, v105, v69
	v_add_f32_e32 v83, 1.0, v83
	v_rcp_f32_e32 v63, v63
	v_add_f32_e32 v64, 1.0, v64
	v_add_f32_e32 v42, 1.0, v42
	v_exp_f32_e32 v28, v28
	v_mul_f32_e32 v29, 0xbfb8aa3b, v29
	v_mul_f32_e32 v19, 0xbfb8aa3b, v19
	v_exp_f32_e32 v10, v10
	v_mul_f32_e32 v11, 0xbfb8aa3b, v11
	v_add_f32_e32 v12, v12, v76
	v_add_f32_e32 v2, v8, v68
	v_mul_f32_e32 v101, v98, v99
	v_lshl_add_u64 v[102:103], v[172:173], 0, v[114:115]
	v_cvt_pk_bf16_f32 v98, v106, v107
	v_rcp_f32_e32 v83, v83
	v_rcp_f32_e32 v64, v64
	v_add_f32_e32 v65, 1.0, v65
	v_add_f32_e32 v51, 1.0, v51
	v_rcp_f32_e32 v42, v42
	v_add_f32_e32 v43, 1.0, v43
	v_exp_f32_e32 v29, v29
	v_exp_f32_e32 v19, v19
	v_exp_f32_e32 v11, v11
	v_mul_f32_e32 v12, 0xbfb8aa3b, v12
	v_add_f32_e32 v13, v13, v77
	v_mul_f32_e32 v8, v2, v3
	v_add_f32_e32 v3, v5, v61
	v_cvt_pk_bf16_f32 v99, v108, v109
	v_cvt_pk_bf16_f32 v100, v110, v111
	v_cvt_pk_bf16_f32 v101, v104, v101
	global_store_dwordx4 v[102:103], v[98:101], off
	v_add_f32_e32 v70, v70, v78
	v_rcp_f32_e32 v65, v65
	v_or_b32_e32 v98, 48, v174
	v_rcp_f32_e32 v51, v51
	v_rcp_f32_e32 v43, v43
	v_add_f32_e32 v44, 1.0, v44
	v_add_f32_e32 v26, 1.0, v26
	v_exp_f32_e32 v12, v12
	v_mul_f32_e32 v13, 0xbfb8aa3b, v13
	v_mul_f32_e32 v3, 0xbfb8aa3b, v3
	v_ashrrev_i32_e32 v99, 31, v98
	v_mul_f32_e32 v62, v70, v62
	v_add_f32_e32 v70, v71, v79
	v_rcp_f32_e32 v44, v44
	v_add_f32_e32 v45, 1.0, v45
	v_add_f32_e32 v35, 1.0, v35
	v_rcp_f32_e32 v26, v26
	v_add_f32_e32 v27, 1.0, v27
	v_exp_f32_e32 v13, v13
	v_exp_f32_e32 v3, v3
	v_lshlrev_b64 v[98:99], 11, v[98:99]
	v_add_f32_e32 v82, v89, v69
	v_mul_f32_e32 v63, v70, v63
	v_add_f32_e32 v70, v72, v80
	v_add_f32_e32 v46, v46, v78
	v_rcp_f32_e32 v45, v45
	v_rcp_f32_e32 v35, v35
	v_rcp_f32_e32 v27, v27
	v_add_f32_e32 v28, 1.0, v28
	v_add_f32_e32 v10, 1.0, v10
	v_mul_f32_e32 v85, v82, v83
	v_lshl_add_u64 v[86:87], v[172:173], 0, v[98:99]
	v_mul_f32_e32 v64, v70, v64
	v_add_f32_e32 v70, v73, v81
	v_add_f32_e32 v50, v57, v69
	v_mul_f32_e32 v42, v46, v42
	v_add_f32_e32 v46, v47, v79
	v_rcp_f32_e32 v28, v28
	v_add_f32_e32 v29, 1.0, v29
	v_add_f32_e32 v19, 1.0, v19
	v_rcp_f32_e32 v10, v10
	v_add_f32_e32 v11, 1.0, v11
	v_cvt_pk_bf16_f32 v82, v90, v91
	v_cvt_pk_bf16_f32 v83, v92, v93
	v_cvt_pk_bf16_f32 v84, v94, v95
	v_cvt_pk_bf16_f32 v85, v88, v85
	global_store_dwordx4 v[86:87], v[82:85], off
	v_mul_f32_e32 v65, v70, v65
	v_mul_f32_e32 v53, v50, v51
	v_cvt_pk_bf16_f32 v50, v62, v63
	v_cvt_pk_bf16_f32 v51, v64, v65
	v_cvt_pk_bf16_f32 v52, v54, v55
	v_add_co_u32_e32 v54, vcc, s67, v130
	v_mul_f32_e32 v43, v46, v43
	v_add_f32_e32 v46, v48, v80
	v_add_f32_e32 v30, v30, v78
	v_rcp_f32_e32 v29, v29
	v_rcp_f32_e32 v19, v19
	v_rcp_f32_e32 v11, v11
	v_add_f32_e32 v12, 1.0, v12
	v_addc_co_u32_e32 v55, vcc, 0, v131, vcc
	v_mul_f32_e32 v44, v46, v44
	v_add_f32_e32 v46, v49, v81
	v_add_f32_e32 v34, v41, v69
	v_mul_f32_e32 v26, v30, v26
	v_add_f32_e32 v30, v31, v79
	v_rcp_f32_e32 v12, v12
	v_add_f32_e32 v13, 1.0, v13
	v_add_f32_e32 v3, 1.0, v3
	v_cvt_pk_bf16_f32 v53, v56, v53
	global_store_dwordx4 v[54:55], v[50:53], off
	v_mul_f32_e32 v45, v46, v45
	v_mul_f32_e32 v37, v34, v35
	v_cvt_pk_bf16_f32 v34, v42, v43
	v_cvt_pk_bf16_f32 v35, v44, v45
	v_cvt_pk_bf16_f32 v36, v38, v39
	v_add_co_u32_e32 v38, vcc, s68, v130
	v_mul_f32_e32 v27, v30, v27
	v_add_f32_e32 v30, v32, v80
	v_add_f32_e32 v14, v14, v78
	v_rcp_f32_e32 v13, v13
	v_rcp_f32_e32 v3, v3
	v_addc_co_u32_e32 v39, vcc, 0, v131, vcc
	v_mul_f32_e32 v28, v30, v28
	v_add_f32_e32 v30, v33, v81
	v_add_f32_e32 v18, v25, v69
	v_mul_f32_e32 v10, v14, v10
	v_add_f32_e32 v14, v15, v79
	v_cvt_pk_bf16_f32 v37, v40, v37
	global_store_dwordx4 v[38:39], v[34:37], off
	v_mul_f32_e32 v29, v30, v29
	v_mul_f32_e32 v21, v18, v19
	v_cvt_pk_bf16_f32 v18, v26, v27
	v_cvt_pk_bf16_f32 v19, v28, v29
	v_cvt_pk_bf16_f32 v20, v22, v23
	v_add_co_u32_e32 v22, vcc, s2, v130
	v_mul_f32_e32 v11, v14, v11
	v_add_f32_e32 v14, v16, v80
	v_addc_co_u32_e32 v23, vcc, 0, v131, vcc
	v_mul_f32_e32 v12, v14, v12
	v_add_f32_e32 v14, v17, v81
	v_add_f32_e32 v2, v9, v69
	v_cvt_pk_bf16_f32 v21, v24, v21
	global_store_dwordx4 v[22:23], v[18:21], off
	v_mul_f32_e32 v13, v14, v13
	v_mul_f32_e32 v5, v2, v3
	v_cvt_pk_bf16_f32 v2, v10, v11
	v_cvt_pk_bf16_f32 v3, v12, v13
	v_cvt_pk_bf16_f32 v4, v6, v7
	v_add_co_u32_e32 v6, vcc, 0x58000, v130
	s_mov_b32 s2, s48
	s_nop 0
	v_addc_co_u32_e32 v7, vcc, 0, v131, vcc
	s_and_b64 vcc, exec, s[38:39]
	v_cvt_pk_bf16_f32 v5, v8, v5
	global_store_dwordx4 v[6:7], v[2:5], off
	s_cbranch_vccz .LBB0_88
	s_waitcnt vmcnt(8)
	s_cmpk_gt_u32 s35, 0xff
	s_cbranch_scc1 .LBB0_99
	s_barrier

.Lkprio_3:
.LBB0_260:
	s_add_u32 s22, s0, 0xfffc0080
	s_addc_u32 s23, s1, -1
	s_add_i32 s60, 0, 0x10000
	v_add_u32_e32 v142, s60, v178
	ds_read_b128 v[130:133], v142
	ds_read_b128 v[134:137], v142 offset:1024
	ds_read_b128 v[138:141], v142 offset:2048
	ds_read_b128 v[142:145], v142 offset:3072
	s_cmp_eq_u32 s59, 12
	s_cselect_b32 s47, s35, s23
	s_cselect_b32 s46, s55, s22
	s_cselect_b32 s23, s31, s58
	s_cselect_b32 s22, s56, s57
	v_lshl_add_u64 v[186:187], s[0:1], 0, v[168:169]
	s_add_i32 m0, s27, 0xc000
	ds_read_b128 v[172:175], v180
	ds_read_b128 v[182:185], v180 offset:1024
	ds_read_b128 v[206:209], v180 offset:2048
	ds_read_b128 v[210:213], v180 offset:3072
	ds_read_b128 v[214:217], v180 offset:4096
	ds_read_b128 v[218:221], v180 offset:5120
	ds_read_b128 v[222:225], v180 offset:6144
	ds_read_b128 v[226:229], v180 offset:7168
	global_load_lds_dwordx4 v[186:187], off
	v_lshl_add_u64 v[186:187], s[0:1], 0, v[170:171]
	s_add_i32 m0, s27, 0xe000
	s_nop 0
	global_load_lds_dwordx4 v[186:187], off
	s_waitcnt lgkmcnt(8)
	s_barrier
	s_waitcnt lgkmcnt(0)
	v_mfma_f32_16x16x32_bf16 v[126:129], v[130:133], v[172:175], v[126:129]
	v_mfma_f32_16x16x32_bf16 v[122:125], v[138:141], v[172:175], v[122:125]
	v_mfma_f32_16x16x32_bf16 v[110:113], v[130:133], v[206:209], v[110:113]
	v_mfma_f32_16x16x32_bf16 v[106:109], v[138:141], v[206:209], v[106:109]
	v_mfma_f32_16x16x32_bf16 v[94:97], v[130:133], v[214:217], v[94:97]
	v_mfma_f32_16x16x32_bf16 v[90:93], v[138:141], v[214:217], v[90:93]
	v_mfma_f32_16x16x32_bf16 v[78:81], v[130:133], v[222:225], v[78:81]
	v_mfma_f32_16x16x32_bf16 v[74:77], v[138:141], v[222:225], v[74:77]
	v_mfma_f32_16x16x32_bf16 v[126:129], v[134:137], v[182:185], v[126:129]
	v_mfma_f32_16x16x32_bf16 v[122:125], v[142:145], v[182:185], v[122:125]
	v_mfma_f32_16x16x32_bf16 v[110:113], v[134:137], v[210:213], v[110:113]
	v_mfma_f32_16x16x32_bf16 v[106:109], v[142:145], v[210:213], v[106:109]
	v_mfma_f32_16x16x32_bf16 v[94:97], v[134:137], v[218:221], v[94:97]
	v_mfma_f32_16x16x32_bf16 v[90:93], v[142:145], v[218:221], v[90:93]
	v_mfma_f32_16x16x32_bf16 v[78:81], v[134:137], v[226:229], v[78:81]
	v_mfma_f32_16x16x32_bf16 v[74:77], v[142:145], v[226:229], v[74:77]
	s_barrier
	s_add_i32 s62, 0, 0x14000
	s_add_i32 s60, s60, s25
	v_add_u32_e32 v181, s62, v178
	v_lshl_add_u64 v[186:187], s[22:23], 0, v[0:1]
	s_mov_b32 m0, s60
	ds_read_b128 v[230:233], v181
	ds_read_b128 v[234:237], v181 offset:1024
	ds_read_b128 v[238:241], v181 offset:2048
	ds_read_b128 v[242:245], v181 offset:3072
	global_load_lds_dwordx4 v[186:187], off
	v_lshl_add_u64 v[246:247], s[22:23], 0, v[162:163]
	s_add_i32 m0, s60, 0x2000
	s_nop 0
	global_load_lds_dwordx4 v[246:247], off
	s_barrier
	s_waitcnt lgkmcnt(0)
	v_mfma_f32_16x16x32_bf16 v[118:121], v[230:233], v[172:175], v[118:121]
	v_mfma_f32_16x16x32_bf16 v[114:117], v[238:241], v[172:175], v[114:117]
	v_mfma_f32_16x16x32_bf16 v[102:105], v[230:233], v[206:209], v[102:105]
	v_mfma_f32_16x16x32_bf16 v[98:101], v[238:241], v[206:209], v[98:101]
	v_mfma_f32_16x16x32_bf16 v[86:89], v[230:233], v[214:217], v[86:89]
	v_mfma_f32_16x16x32_bf16 v[82:85], v[238:241], v[214:217], v[82:85]
	v_mfma_f32_16x16x32_bf16 v[70:73], v[230:233], v[222:225], v[70:73]
	v_mfma_f32_16x16x32_bf16 v[66:69], v[238:241], v[222:225], v[66:69]
	v_mfma_f32_16x16x32_bf16 v[118:121], v[234:237], v[182:185], v[118:121]
	v_mfma_f32_16x16x32_bf16 v[114:117], v[242:245], v[182:185], v[114:117]
	v_mfma_f32_16x16x32_bf16 v[102:105], v[234:237], v[210:213], v[102:105]
	v_mfma_f32_16x16x32_bf16 v[98:101], v[242:245], v[210:213], v[98:101]
	v_mfma_f32_16x16x32_bf16 v[86:89], v[234:237], v[218:221], v[86:89]
	v_mfma_f32_16x16x32_bf16 v[82:85], v[242:245], v[218:221], v[82:85]
	v_mfma_f32_16x16x32_bf16 v[70:73], v[234:237], v[226:229], v[70:73]
	v_mfma_f32_16x16x32_bf16 v[66:69], v[242:245], v[226:229], v[66:69]
	s_barrier
	s_mov_b32 m0, s27
	v_lshl_add_u64 v[248:249], s[46:47], 0, v[166:167]
	ds_read_b128 v[172:175], v180 offset:16384
	ds_read_b128 v[182:185], v180 offset:17408
	ds_read_b128 v[206:209], v180 offset:18432
	ds_read_b128 v[210:213], v180 offset:19456
	ds_read_b128 v[214:217], v180 offset:20480
	ds_read_b128 v[218:221], v180 offset:21504
	ds_read_b128 v[222:225], v180 offset:22528
	ds_read_b128 v[226:229], v180 offset:23552
	global_load_lds_dwordx4 v[248:249], off
	v_lshl_add_u64 v[250:251], s[46:47], 0, v[164:165]
	s_mov_b32 m0, s45
	s_nop 0
	global_load_lds_dwordx4 v[250:251], off
	s_barrier
	s_waitcnt lgkmcnt(0)
	v_mfma_f32_16x16x32_bf16 v[62:65], v[130:133], v[172:175], v[62:65]
	v_mfma_f32_16x16x32_bf16 v[58:61], v[138:141], v[172:175], v[58:61]
	v_mfma_f32_16x16x32_bf16 v[50:53], v[130:133], v[206:209], v[50:53]
	v_mfma_f32_16x16x32_bf16 v[42:45], v[138:141], v[206:209], v[42:45]
	v_mfma_f32_16x16x32_bf16 v[34:37], v[130:133], v[214:217], v[34:37]
	v_mfma_f32_16x16x32_bf16 v[26:29], v[138:141], v[214:217], v[26:29]
	v_mfma_f32_16x16x32_bf16 v[18:21], v[130:133], v[222:225], v[18:21]
	v_mfma_f32_16x16x32_bf16 v[10:13], v[138:141], v[222:225], v[10:13]
	v_mfma_f32_16x16x32_bf16 v[62:65], v[134:137], v[182:185], v[62:65]
	v_mfma_f32_16x16x32_bf16 v[58:61], v[142:145], v[182:185], v[58:61]
	v_mfma_f32_16x16x32_bf16 v[50:53], v[134:137], v[210:213], v[50:53]
	v_mfma_f32_16x16x32_bf16 v[42:45], v[142:145], v[210:213], v[42:45]
	v_mfma_f32_16x16x32_bf16 v[34:37], v[134:137], v[218:221], v[34:37]
	v_mfma_f32_16x16x32_bf16 v[26:29], v[142:145], v[218:221], v[26:29]
	v_mfma_f32_16x16x32_bf16 v[18:21], v[134:137], v[226:229], v[18:21]
	v_mfma_f32_16x16x32_bf16 v[10:13], v[142:145], v[226:229], v[10:13]
	s_barrier
	s_add_u32 s60, s22, 0x40000
	s_addc_u32 s61, s23, 0
	s_add_i32 s62, s62, s25
	v_lshl_add_u64 v[130:131], s[60:61], 0, v[0:1]
	s_mov_b32 m0, s62
	s_nop 0
	global_load_lds_dwordx4 v[130:131], off
	v_lshl_add_u64 v[130:131], s[60:61], 0, v[162:163]
	s_add_i32 m0, s62, 0x2000
	s_nop 0
	global_load_lds_dwordx4 v[130:131], off
	s_waitcnt vmcnt(6)
	s_barrier
	v_mfma_f32_16x16x32_bf16 v[54:57], v[230:233], v[172:175], v[54:57]
	v_mfma_f32_16x16x32_bf16 v[46:49], v[238:241], v[172:175], v[46:49]
	v_mfma_f32_16x16x32_bf16 v[38:41], v[230:233], v[206:209], v[38:41]
	v_mfma_f32_16x16x32_bf16 v[30:33], v[238:241], v[206:209], v[30:33]
	v_mfma_f32_16x16x32_bf16 v[22:25], v[230:233], v[214:217], v[22:25]
	v_mfma_f32_16x16x32_bf16 v[14:17], v[238:241], v[214:217], v[14:17]
	v_mfma_f32_16x16x32_bf16 v[6:9], v[230:233], v[222:225], v[6:9]
	v_mfma_f32_16x16x32_bf16 v[2:5], v[238:241], v[222:225], v[2:5]
	v_mfma_f32_16x16x32_bf16 v[54:57], v[234:237], v[182:185], v[54:57]
	v_mfma_f32_16x16x32_bf16 v[46:49], v[242:245], v[182:185], v[46:49]
	v_mfma_f32_16x16x32_bf16 v[38:41], v[234:237], v[210:213], v[38:41]
	v_mfma_f32_16x16x32_bf16 v[30:33], v[242:245], v[210:213], v[30:33]
	v_mfma_f32_16x16x32_bf16 v[22:25], v[234:237], v[218:221], v[22:25]
	v_mfma_f32_16x16x32_bf16 v[14:17], v[242:245], v[218:221], v[14:17]
	v_mfma_f32_16x16x32_bf16 v[6:9], v[234:237], v[226:229], v[6:9]
	v_mfma_f32_16x16x32_bf16 v[2:5], v[242:245], v[226:229], v[2:5]
	s_barrier
	s_add_i32 s60, 0, 0x18000
	v_add_u32_e32 v142, s60, v178
	ds_read_b128 v[130:133], v142
	ds_read_b128 v[134:137], v142 offset:1024
	ds_read_b128 v[138:141], v142 offset:2048
	ds_read_b128 v[142:145], v142 offset:3072
	s_add_u32 s46, s46, 0x40000
	s_addc_u32 s47, s47, 0
	s_mov_b32 m0, s48
	v_lshl_add_u64 v[230:231], s[46:47], 0, v[166:167]
	ds_read_b128 v[172:175], v180 offset:32768
	ds_read_b128 v[182:185], v180 offset:33792
	ds_read_b128 v[206:209], v180 offset:34816
	ds_read_b128 v[210:213], v180 offset:35840
	ds_read_b128 v[214:217], v180 offset:36864
	ds_read_b128 v[218:221], v180 offset:37888
	ds_read_b128 v[222:225], v180 offset:38912
	ds_read_b128 v[226:229], v180 offset:39936
	global_load_lds_dwordx4 v[230:231], off
	v_lshl_add_u64 v[230:231], s[46:47], 0, v[164:165]
	s_mov_b32 m0, s49
	s_nop 0
	global_load_lds_dwordx4 v[230:231], off
	s_waitcnt lgkmcnt(8)
	s_barrier
	s_waitcnt lgkmcnt(0)
	v_mfma_f32_16x16x32_bf16 v[126:129], v[130:133], v[172:175], v[126:129]
	v_mfma_f32_16x16x32_bf16 v[122:125], v[138:141], v[172:175], v[122:125]
	v_mfma_f32_16x16x32_bf16 v[110:113], v[130:133], v[206:209], v[110:113]
	v_mfma_f32_16x16x32_bf16 v[106:109], v[138:141], v[206:209], v[106:109]
	v_mfma_f32_16x16x32_bf16 v[94:97], v[130:133], v[214:217], v[94:97]
	v_mfma_f32_16x16x32_bf16 v[90:93], v[138:141], v[214:217], v[90:93]
	v_mfma_f32_16x16x32_bf16 v[78:81], v[130:133], v[222:225], v[78:81]
	v_mfma_f32_16x16x32_bf16 v[74:77], v[138:141], v[222:225], v[74:77]
	v_mfma_f32_16x16x32_bf16 v[126:129], v[134:137], v[182:185], v[126:129]
	v_mfma_f32_16x16x32_bf16 v[122:125], v[142:145], v[182:185], v[122:125]
	v_mfma_f32_16x16x32_bf16 v[110:113], v[134:137], v[210:213], v[110:113]
	v_mfma_f32_16x16x32_bf16 v[106:109], v[142:145], v[210:213], v[106:109]
	v_mfma_f32_16x16x32_bf16 v[94:97], v[134:137], v[218:221], v[94:97]
	v_mfma_f32_16x16x32_bf16 v[90:93], v[142:145], v[218:221], v[90:93]
	v_mfma_f32_16x16x32_bf16 v[78:81], v[134:137], v[226:229], v[78:81]
	v_mfma_f32_16x16x32_bf16 v[74:77], v[142:145], v[226:229], v[74:77]
	s_barrier
	s_add_i32 s46, 0, 0x1c000
	s_add_i32 s47, s60, s25
	v_add_u32_e32 v181, s46, v178
	v_lshl_add_u64 v[186:187], v[186:187], 0, s[94:95]
	s_mov_b32 m0, s47
	ds_read_b128 v[230:233], v181
	ds_read_b128 v[234:237], v181 offset:1024
	ds_read_b128 v[238:241], v181 offset:2048
	ds_read_b128 v[242:245], v181 offset:3072
	global_load_lds_dwordx4 v[186:187], off
	v_lshl_add_u64 v[186:187], v[246:247], 0, s[94:95]
	s_add_i32 m0, s47, 0x2000
	s_nop 0
	global_load_lds_dwordx4 v[186:187], off
	s_barrier
	s_waitcnt lgkmcnt(0)
	v_mfma_f32_16x16x32_bf16 v[118:121], v[230:233], v[172:175], v[118:121]
	v_mfma_f32_16x16x32_bf16 v[114:117], v[238:241], v[172:175], v[114:117]
	v_mfma_f32_16x16x32_bf16 v[102:105], v[230:233], v[206:209], v[102:105]
	v_mfma_f32_16x16x32_bf16 v[98:101], v[238:241], v[206:209], v[98:101]
	v_mfma_f32_16x16x32_bf16 v[86:89], v[230:233], v[214:217], v[86:89]
	v_mfma_f32_16x16x32_bf16 v[82:85], v[238:241], v[214:217], v[82:85]
	v_mfma_f32_16x16x32_bf16 v[70:73], v[230:233], v[222:225], v[70:73]
	v_mfma_f32_16x16x32_bf16 v[66:69], v[238:241], v[222:225], v[66:69]
	v_mfma_f32_16x16x32_bf16 v[118:121], v[234:237], v[182:185], v[118:121]
	v_mfma_f32_16x16x32_bf16 v[114:117], v[242:245], v[182:185], v[114:117]
	v_mfma_f32_16x16x32_bf16 v[102:105], v[234:237], v[210:213], v[102:105]
	v_mfma_f32_16x16x32_bf16 v[98:101], v[242:245], v[210:213], v[98:101]
	v_mfma_f32_16x16x32_bf16 v[86:89], v[234:237], v[218:221], v[86:89]
	v_mfma_f32_16x16x32_bf16 v[82:85], v[242:245], v[218:221], v[82:85]
	v_mfma_f32_16x16x32_bf16 v[70:73], v[234:237], v[226:229], v[70:73]
	v_mfma_f32_16x16x32_bf16 v[66:69], v[242:245], v[226:229], v[66:69]
	s_barrier
	s_mov_b32 m0, s51
	v_lshl_add_u64 v[186:187], v[248:249], 0, s[94:95]
	ds_read_b128 v[172:175], v180 offset:49152
	ds_read_b128 v[182:185], v180 offset:50176
	ds_read_b128 v[206:209], v180 offset:51200
	ds_read_b128 v[210:213], v180 offset:52224
	ds_read_b128 v[214:217], v180 offset:53248
	ds_read_b128 v[218:221], v180 offset:54272
	ds_read_b128 v[222:225], v180 offset:55296
	ds_read_b128 v[226:229], v180 offset:56320
	global_load_lds_dwordx4 v[186:187], off
	v_lshl_add_u64 v[186:187], v[250:251], 0, s[94:95]
	s_mov_b32 m0, s52
	s_nop 0
	global_load_lds_dwordx4 v[186:187], off
	s_barrier
	s_waitcnt lgkmcnt(0)
	v_mfma_f32_16x16x32_bf16 v[62:65], v[130:133], v[172:175], v[62:65]
	v_mfma_f32_16x16x32_bf16 v[58:61], v[138:141], v[172:175], v[58:61]
	v_mfma_f32_16x16x32_bf16 v[50:53], v[130:133], v[206:209], v[50:53]
	v_mfma_f32_16x16x32_bf16 v[42:45], v[138:141], v[206:209], v[42:45]
	v_mfma_f32_16x16x32_bf16 v[34:37], v[130:133], v[214:217], v[34:37]
	v_mfma_f32_16x16x32_bf16 v[26:29], v[138:141], v[214:217], v[26:29]
	v_mfma_f32_16x16x32_bf16 v[18:21], v[130:133], v[222:225], v[18:21]
	v_mfma_f32_16x16x32_bf16 v[10:13], v[138:141], v[222:225], v[10:13]
	v_mfma_f32_16x16x32_bf16 v[62:65], v[134:137], v[182:185], v[62:65]
	v_mfma_f32_16x16x32_bf16 v[58:61], v[142:145], v[182:185], v[58:61]
	v_mfma_f32_16x16x32_bf16 v[50:53], v[134:137], v[210:213], v[50:53]
	v_mfma_f32_16x16x32_bf16 v[42:45], v[142:145], v[210:213], v[42:45]
	v_mfma_f32_16x16x32_bf16 v[34:37], v[134:137], v[218:221], v[34:37]
	v_mfma_f32_16x16x32_bf16 v[26:29], v[142:145], v[218:221], v[26:29]
	v_mfma_f32_16x16x32_bf16 v[18:21], v[134:137], v[226:229], v[18:21]
	v_mfma_f32_16x16x32_bf16 v[10:13], v[142:145], v[226:229], v[10:13]
	s_barrier
	s_add_u32 s22, s22, 0x40080
	s_addc_u32 s23, s23, 0
	s_add_i32 s46, s46, s25
	v_lshl_add_u64 v[130:131], s[22:23], 0, v[0:1]
	s_mov_b32 m0, s46
	s_nop 0
	global_load_lds_dwordx4 v[130:131], off
	v_lshl_add_u64 v[130:131], s[22:23], 0, v[162:163]
	s_add_i32 m0, s46, 0x2000
	s_nop 0
	global_load_lds_dwordx4 v[130:131], off
	s_waitcnt vmcnt(6)
	s_barrier
	v_mfma_f32_16x16x32_bf16 v[54:57], v[230:233], v[172:175], v[54:57]
	v_mfma_f32_16x16x32_bf16 v[46:49], v[238:241], v[172:175], v[46:49]
	v_mfma_f32_16x16x32_bf16 v[38:41], v[230:233], v[206:209], v[38:41]
	v_mfma_f32_16x16x32_bf16 v[30:33], v[238:241], v[206:209], v[30:33]
	v_mfma_f32_16x16x32_bf16 v[22:25], v[230:233], v[214:217], v[22:25]
	v_mfma_f32_16x16x32_bf16 v[14:17], v[238:241], v[214:217], v[14:17]
	v_mfma_f32_16x16x32_bf16 v[6:9], v[230:233], v[222:225], v[6:9]
	v_mfma_f32_16x16x32_bf16 v[2:5], v[238:241], v[222:225], v[2:5]
	v_mfma_f32_16x16x32_bf16 v[54:57], v[234:237], v[182:185], v[54:57]
	v_mfma_f32_16x16x32_bf16 v[46:49], v[242:245], v[182:185], v[46:49]
	v_mfma_f32_16x16x32_bf16 v[38:41], v[234:237], v[210:213], v[38:41]
	v_mfma_f32_16x16x32_bf16 v[30:33], v[242:245], v[210:213], v[30:33]
	v_mfma_f32_16x16x32_bf16 v[22:25], v[234:237], v[218:221], v[22:25]
	v_mfma_f32_16x16x32_bf16 v[14:17], v[242:245], v[218:221], v[14:17]
	v_mfma_f32_16x16x32_bf16 v[6:9], v[234:237], v[226:229], v[6:9]
	v_mfma_f32_16x16x32_bf16 v[2:5], v[242:245], v[226:229], v[2:5]
	s_barrier
	s_add_i32 s59, s59, 2
	s_add_u32 s0, s0, 0x100
	s_addc_u32 s1, s1, 0
	s_add_u32 s57, s57, 0x100
	s_addc_u32 s58, s58, 0
	s_cmp_gt_u32 s59, 13
	s_cbranch_scc0 .LBB0_260
	v_lshl_or_b32 v172, s54, 8, v179
	v_ashrrev_i32_e32 v173, 31, v172
	v_cndmask_b32_e64 v131, 0, 1, s[2:3]
	v_lshl_add_u64 v[174:175], v[172:173], 2, s[8:9]
	v_mov_b32_e32 v130, 0
	v_cmp_ne_u32_e64 s[0:1], 1, v131
	s_andn2_b64 vcc, exec, s[2:3]
	v_mov_b32_e32 v134, 0
	v_mov_b32_e32 v135, 0
	v_mov_b32_e32 v136, 0
	v_mov_b32_e32 v137, 0
	s_cbranch_vccnz .LBB0_263
	global_load_dwordx4 v[134:137], v[174:175], off

.Lkprio_2:
.LBB0_331:
	s_add_u32 s22, s24, 0x100
	s_addc_u32 s23, s25, 0
	s_add_i32 s52, 0, 0x10000
	v_add_u32_e32 v140, s52, v144
	ds_read_b128 v[164:167], v140
	ds_read_b128 v[168:171], v140 offset:1024
	ds_read_b128 v[172:175], v140 offset:2048
	ds_read_b128 v[176:179], v140 offset:3072
	s_cmp_eq_u32 s51, 40
	s_cselect_b32 s29, s3, s23
	s_cselect_b32 s28, s2, s22
	s_cselect_b32 s27, s1, s41
	s_cselect_b32 s26, s0, s40
	v_lshl_add_u64 v[140:141], s[24:25], 0, v[136:137]
	s_add_i32 m0, s35, 0xc000
	ds_read_b128 v[180:183], v162
	ds_read_b128 v[184:187], v162 offset:1024
	ds_read_b128 v[206:209], v162 offset:2048
	ds_read_b128 v[210:213], v162 offset:3072
	ds_read_b128 v[214:217], v162 offset:4096
	ds_read_b128 v[218:221], v162 offset:5120
	ds_read_b128 v[222:225], v162 offset:6144
	ds_read_b128 v[226:229], v162 offset:7168
	global_load_lds_dwordx4 v[140:141], off
	v_lshl_add_u64 v[140:141], s[24:25], 0, v[138:139]
	s_add_i32 m0, s35, 0xe000
	s_nop 0
	global_load_lds_dwordx4 v[140:141], off
	s_waitcnt lgkmcnt(8)
	s_barrier
	s_waitcnt lgkmcnt(0)
	v_mfma_f32_16x16x32_bf16 v[126:129], v[164:167], v[180:183], v[126:129]
	v_mfma_f32_16x16x32_bf16 v[122:125], v[172:175], v[180:183], v[122:125]
	v_mfma_f32_16x16x32_bf16 v[114:117], v[164:167], v[206:209], v[114:117]
	v_mfma_f32_16x16x32_bf16 v[106:109], v[172:175], v[206:209], v[106:109]
	v_mfma_f32_16x16x32_bf16 v[98:101], v[164:167], v[214:217], v[98:101]
	v_mfma_f32_16x16x32_bf16 v[90:93], v[172:175], v[214:217], v[90:93]
	v_mfma_f32_16x16x32_bf16 v[82:85], v[164:167], v[222:225], v[82:85]
	v_mfma_f32_16x16x32_bf16 v[74:77], v[172:175], v[222:225], v[74:77]
	v_mfma_f32_16x16x32_bf16 v[126:129], v[168:171], v[184:187], v[126:129]
	v_mfma_f32_16x16x32_bf16 v[122:125], v[176:179], v[184:187], v[122:125]
	v_mfma_f32_16x16x32_bf16 v[114:117], v[168:171], v[210:213], v[114:117]
	v_mfma_f32_16x16x32_bf16 v[106:109], v[176:179], v[210:213], v[106:109]
	v_mfma_f32_16x16x32_bf16 v[98:101], v[168:171], v[218:221], v[98:101]
	v_mfma_f32_16x16x32_bf16 v[90:93], v[176:179], v[218:221], v[90:93]
	v_mfma_f32_16x16x32_bf16 v[82:85], v[168:171], v[226:229], v[82:85]
	v_mfma_f32_16x16x32_bf16 v[74:77], v[176:179], v[226:229], v[74:77]
	s_barrier
	s_add_i32 s53, 0, 0x14000
	v_add_u32_e32 v140, s53, v144
	s_add_i32 s24, s52, s31
	ds_read_b128 v[230:233], v140
	ds_read_b128 v[234:237], v140 offset:1024
	ds_read_b128 v[238:241], v140 offset:2048
	ds_read_b128 v[242:245], v140 offset:3072
	v_lshl_add_u64 v[140:141], s[26:27], 0, v[0:1]
	s_mov_b32 m0, s24
	v_lshl_add_u64 v[246:247], s[26:27], 0, v[130:131]
	global_load_lds_dwordx4 v[140:141], off
	s_add_i32 m0, s24, 0x2000
	s_nop 0
	global_load_lds_dwordx4 v[246:247], off
	s_barrier
	s_waitcnt lgkmcnt(0)
	v_mfma_f32_16x16x32_bf16 v[118:121], v[230:233], v[180:183], v[118:121]
	v_mfma_f32_16x16x32_bf16 v[110:113], v[238:241], v[180:183], v[110:113]
	v_mfma_f32_16x16x32_bf16 v[102:105], v[230:233], v[206:209], v[102:105]
	v_mfma_f32_16x16x32_bf16 v[94:97], v[238:241], v[206:209], v[94:97]
	v_mfma_f32_16x16x32_bf16 v[86:89], v[230:233], v[214:217], v[86:89]
	v_mfma_f32_16x16x32_bf16 v[78:81], v[238:241], v[214:217], v[78:81]
	v_mfma_f32_16x16x32_bf16 v[70:73], v[230:233], v[222:225], v[70:73]
	v_mfma_f32_16x16x32_bf16 v[66:69], v[238:241], v[222:225], v[66:69]
	v_mfma_f32_16x16x32_bf16 v[118:121], v[234:237], v[184:187], v[118:121]
	v_mfma_f32_16x16x32_bf16 v[110:113], v[242:245], v[184:187], v[110:113]
	v_mfma_f32_16x16x32_bf16 v[102:105], v[234:237], v[210:213], v[102:105]
	v_mfma_f32_16x16x32_bf16 v[94:97], v[242:245], v[210:213], v[94:97]
	v_mfma_f32_16x16x32_bf16 v[86:89], v[234:237], v[218:221], v[86:89]
	v_mfma_f32_16x16x32_bf16 v[78:81], v[242:245], v[218:221], v[78:81]
	v_mfma_f32_16x16x32_bf16 v[70:73], v[234:237], v[226:229], v[70:73]
	v_mfma_f32_16x16x32_bf16 v[66:69], v[242:245], v[226:229], v[66:69]
	s_barrier
	s_mov_b32 m0, s35
	v_lshl_add_u64 v[248:249], s[28:29], 0, v[134:135]
	ds_read_b128 v[180:183], v162 offset:16384
	ds_read_b128 v[184:187], v162 offset:17408
	ds_read_b128 v[206:209], v162 offset:18432
	ds_read_b128 v[210:213], v162 offset:19456
	ds_read_b128 v[214:217], v162 offset:20480
	ds_read_b128 v[218:221], v162 offset:21504
	ds_read_b128 v[222:225], v162 offset:22528
	ds_read_b128 v[226:229], v162 offset:23552
	global_load_lds_dwordx4 v[248:249], off
	v_lshl_add_u64 v[250:251], s[28:29], 0, v[132:133]
	s_mov_b32 m0, s36
	s_nop 0
	global_load_lds_dwordx4 v[250:251], off
	s_barrier
	s_waitcnt lgkmcnt(0)
	v_mfma_f32_16x16x32_bf16 v[62:65], v[164:167], v[180:183], v[62:65]
	v_mfma_f32_16x16x32_bf16 v[58:61], v[172:175], v[180:183], v[58:61]
	v_mfma_f32_16x16x32_bf16 v[50:53], v[164:167], v[206:209], v[50:53]
	v_mfma_f32_16x16x32_bf16 v[42:45], v[172:175], v[206:209], v[42:45]
	v_mfma_f32_16x16x32_bf16 v[34:37], v[164:167], v[214:217], v[34:37]
	v_mfma_f32_16x16x32_bf16 v[26:29], v[172:175], v[214:217], v[26:29]
	v_mfma_f32_16x16x32_bf16 v[18:21], v[164:167], v[222:225], v[18:21]
	v_mfma_f32_16x16x32_bf16 v[10:13], v[172:175], v[222:225], v[10:13]
	v_mfma_f32_16x16x32_bf16 v[62:65], v[168:171], v[184:187], v[62:65]
	v_mfma_f32_16x16x32_bf16 v[58:61], v[176:179], v[184:187], v[58:61]
	v_mfma_f32_16x16x32_bf16 v[50:53], v[168:171], v[210:213], v[50:53]
	v_mfma_f32_16x16x32_bf16 v[42:45], v[176:179], v[210:213], v[42:45]
	v_mfma_f32_16x16x32_bf16 v[34:37], v[168:171], v[218:221], v[34:37]
	v_mfma_f32_16x16x32_bf16 v[26:29], v[176:179], v[218:221], v[26:29]
	v_mfma_f32_16x16x32_bf16 v[18:21], v[168:171], v[226:229], v[18:21]
	v_mfma_f32_16x16x32_bf16 v[10:13], v[176:179], v[226:229], v[10:13]
	s_barrier
	s_add_u32 s24, s26, 0xb0000
	s_addc_u32 s25, s27, 0
	s_add_i32 s52, s53, s31
	v_lshl_add_u64 v[164:165], s[24:25], 0, v[0:1]
	s_mov_b32 m0, s52
	s_nop 0
	global_load_lds_dwordx4 v[164:165], off
	v_lshl_add_u64 v[164:165], s[24:25], 0, v[130:131]
	s_add_i32 m0, s52, 0x2000
	s_nop 0
	global_load_lds_dwordx4 v[164:165], off
	s_waitcnt vmcnt(6)
	s_barrier
	v_mfma_f32_16x16x32_bf16 v[54:57], v[230:233], v[180:183], v[54:57]
	v_mfma_f32_16x16x32_bf16 v[46:49], v[238:241], v[180:183], v[46:49]
	v_mfma_f32_16x16x32_bf16 v[38:41], v[230:233], v[206:209], v[38:41]
	v_mfma_f32_16x16x32_bf16 v[30:33], v[238:241], v[206:209], v[30:33]
	v_mfma_f32_16x16x32_bf16 v[22:25], v[230:233], v[214:217], v[22:25]
	v_mfma_f32_16x16x32_bf16 v[14:17], v[238:241], v[214:217], v[14:17]
	v_mfma_f32_16x16x32_bf16 v[6:9], v[230:233], v[222:225], v[6:9]
	v_mfma_f32_16x16x32_bf16 v[2:5], v[238:241], v[222:225], v[2:5]
	v_mfma_f32_16x16x32_bf16 v[54:57], v[234:237], v[184:187], v[54:57]
	v_mfma_f32_16x16x32_bf16 v[46:49], v[242:245], v[184:187], v[46:49]
	v_mfma_f32_16x16x32_bf16 v[38:41], v[234:237], v[210:213], v[38:41]
	v_mfma_f32_16x16x32_bf16 v[30:33], v[242:245], v[210:213], v[30:33]
	v_mfma_f32_16x16x32_bf16 v[22:25], v[234:237], v[218:221], v[22:25]
	v_mfma_f32_16x16x32_bf16 v[14:17], v[242:245], v[218:221], v[14:17]
	v_mfma_f32_16x16x32_bf16 v[6:9], v[234:237], v[226:229], v[6:9]
	v_mfma_f32_16x16x32_bf16 v[2:5], v[242:245], v[226:229], v[2:5]
	s_barrier
	s_add_i32 s52, 0, 0x18000
	v_add_u32_e32 v163, s52, v144
	ds_read_b128 v[164:167], v163
	ds_read_b128 v[168:171], v163 offset:1024
	ds_read_b128 v[172:175], v163 offset:2048
	ds_read_b128 v[176:179], v163 offset:3072
	s_add_u32 s24, s28, 0xb0000
	s_addc_u32 s25, s29, 0
	s_mov_b32 m0, s37
	v_lshl_add_u64 v[230:231], s[24:25], 0, v[134:135]
	ds_read_b128 v[180:183], v162 offset:32768
	ds_read_b128 v[184:187], v162 offset:33792
	ds_read_b128 v[206:209], v162 offset:34816
	ds_read_b128 v[210:213], v162 offset:35840
	ds_read_b128 v[214:217], v162 offset:36864
	ds_read_b128 v[218:221], v162 offset:37888
	ds_read_b128 v[222:225], v162 offset:38912
	ds_read_b128 v[226:229], v162 offset:39936
	global_load_lds_dwordx4 v[230:231], off
	v_lshl_add_u64 v[230:231], s[24:25], 0, v[132:133]
	s_mov_b32 m0, s42
	s_nop 0
	global_load_lds_dwordx4 v[230:231], off
	s_waitcnt lgkmcnt(8)
	s_barrier
	s_waitcnt lgkmcnt(0)
	v_mfma_f32_16x16x32_bf16 v[126:129], v[164:167], v[180:183], v[126:129]
	v_mfma_f32_16x16x32_bf16 v[122:125], v[172:175], v[180:183], v[122:125]
	v_mfma_f32_16x16x32_bf16 v[114:117], v[164:167], v[206:209], v[114:117]
	v_mfma_f32_16x16x32_bf16 v[106:109], v[172:175], v[206:209], v[106:109]
	v_mfma_f32_16x16x32_bf16 v[98:101], v[164:167], v[214:217], v[98:101]
	v_mfma_f32_16x16x32_bf16 v[90:93], v[172:175], v[214:217], v[90:93]
	v_mfma_f32_16x16x32_bf16 v[82:85], v[164:167], v[222:225], v[82:85]
	v_mfma_f32_16x16x32_bf16 v[74:77], v[172:175], v[222:225], v[74:77]
	v_mfma_f32_16x16x32_bf16 v[126:129], v[168:171], v[184:187], v[126:129]
	v_mfma_f32_16x16x32_bf16 v[122:125], v[176:179], v[184:187], v[122:125]
	v_mfma_f32_16x16x32_bf16 v[114:117], v[168:171], v[210:213], v[114:117]
	v_mfma_f32_16x16x32_bf16 v[106:109], v[176:179], v[210:213], v[106:109]
	v_mfma_f32_16x16x32_bf16 v[98:101], v[168:171], v[218:221], v[98:101]
	v_mfma_f32_16x16x32_bf16 v[90:93], v[176:179], v[218:221], v[90:93]
	v_mfma_f32_16x16x32_bf16 v[82:85], v[168:171], v[226:229], v[82:85]
	v_mfma_f32_16x16x32_bf16 v[74:77], v[176:179], v[226:229], v[74:77]
	s_barrier
	s_add_i32 s28, 0, 0x1c000
	s_add_i32 s24, s52, s31
	v_add_u32_e32 v163, s28, v144
	v_lshl_add_u64 v[140:141], v[140:141], 0, s[94:95]
	s_mov_b32 m0, s24
	ds_read_b128 v[230:233], v163
	ds_read_b128 v[234:237], v163 offset:1024
	ds_read_b128 v[238:241], v163 offset:2048
	ds_read_b128 v[242:245], v163 offset:3072
	global_load_lds_dwordx4 v[140:141], off
	v_lshl_add_u64 v[140:141], v[246:247], 0, s[94:95]
	s_add_i32 m0, s24, 0x2000
	s_nop 0
	global_load_lds_dwordx4 v[140:141], off
	s_barrier
	s_waitcnt lgkmcnt(0)
	v_mfma_f32_16x16x32_bf16 v[118:121], v[230:233], v[180:183], v[118:121]
	v_mfma_f32_16x16x32_bf16 v[110:113], v[238:241], v[180:183], v[110:113]
	v_mfma_f32_16x16x32_bf16 v[102:105], v[230:233], v[206:209], v[102:105]
	v_mfma_f32_16x16x32_bf16 v[94:97], v[238:241], v[206:209], v[94:97]
	v_mfma_f32_16x16x32_bf16 v[86:89], v[230:233], v[214:217], v[86:89]
	v_mfma_f32_16x16x32_bf16 v[78:81], v[238:241], v[214:217], v[78:81]
	v_mfma_f32_16x16x32_bf16 v[70:73], v[230:233], v[222:225], v[70:73]
	v_mfma_f32_16x16x32_bf16 v[66:69], v[238:241], v[222:225], v[66:69]
	v_mfma_f32_16x16x32_bf16 v[118:121], v[234:237], v[184:187], v[118:121]
	v_mfma_f32_16x16x32_bf16 v[110:113], v[242:245], v[184:187], v[110:113]
	v_mfma_f32_16x16x32_bf16 v[102:105], v[234:237], v[210:213], v[102:105]
	v_mfma_f32_16x16x32_bf16 v[94:97], v[242:245], v[210:213], v[94:97]
	v_mfma_f32_16x16x32_bf16 v[86:89], v[234:237], v[218:221], v[86:89]
	v_mfma_f32_16x16x32_bf16 v[78:81], v[242:245], v[218:221], v[78:81]
	v_mfma_f32_16x16x32_bf16 v[70:73], v[234:237], v[226:229], v[70:73]
	v_mfma_f32_16x16x32_bf16 v[66:69], v[242:245], v[226:229], v[66:69]
	s_barrier
	s_mov_b32 m0, s44
	v_lshl_add_u64 v[140:141], v[248:249], 0, s[94:95]
	ds_read_b128 v[180:183], v162 offset:49152
	ds_read_b128 v[184:187], v162 offset:50176
	ds_read_b128 v[206:209], v162 offset:51200
	ds_read_b128 v[210:213], v162 offset:52224
	ds_read_b128 v[214:217], v162 offset:53248
	ds_read_b128 v[218:221], v162 offset:54272
	ds_read_b128 v[222:225], v162 offset:55296
	ds_read_b128 v[226:229], v162 offset:56320
	global_load_lds_dwordx4 v[140:141], off
	v_lshl_add_u64 v[140:141], v[250:251], 0, s[94:95]
	s_mov_b32 m0, s45
	s_nop 0
	global_load_lds_dwordx4 v[140:141], off
	s_barrier
	s_waitcnt lgkmcnt(0)
	v_mfma_f32_16x16x32_bf16 v[62:65], v[164:167], v[180:183], v[62:65]
	v_mfma_f32_16x16x32_bf16 v[58:61], v[172:175], v[180:183], v[58:61]
	v_mfma_f32_16x16x32_bf16 v[50:53], v[164:167], v[206:209], v[50:53]
	v_mfma_f32_16x16x32_bf16 v[42:45], v[172:175], v[206:209], v[42:45]
	v_mfma_f32_16x16x32_bf16 v[34:37], v[164:167], v[214:217], v[34:37]
	v_mfma_f32_16x16x32_bf16 v[26:29], v[172:175], v[214:217], v[26:29]
	v_mfma_f32_16x16x32_bf16 v[18:21], v[164:167], v[222:225], v[18:21]
	v_mfma_f32_16x16x32_bf16 v[10:13], v[172:175], v[222:225], v[10:13]
	v_mfma_f32_16x16x32_bf16 v[62:65], v[168:171], v[184:187], v[62:65]
	v_mfma_f32_16x16x32_bf16 v[58:61], v[176:179], v[184:187], v[58:61]
	v_mfma_f32_16x16x32_bf16 v[50:53], v[168:171], v[210:213], v[50:53]
	v_mfma_f32_16x16x32_bf16 v[42:45], v[176:179], v[210:213], v[42:45]
	v_mfma_f32_16x16x32_bf16 v[34:37], v[168:171], v[218:221], v[34:37]
	v_mfma_f32_16x16x32_bf16 v[26:29], v[176:179], v[218:221], v[26:29]
	v_mfma_f32_16x16x32_bf16 v[18:21], v[168:171], v[226:229], v[18:21]
	v_mfma_f32_16x16x32_bf16 v[10:13], v[176:179], v[226:229], v[10:13]
	s_barrier
	s_add_u32 s24, s26, 0xb0080
	s_addc_u32 s25, s27, 0
	s_add_i32 s26, s28, s31
	v_lshl_add_u64 v[140:141], s[24:25], 0, v[0:1]
	s_mov_b32 m0, s26
	s_nop 0
	global_load_lds_dwordx4 v[140:141], off
	v_lshl_add_u64 v[140:141], s[24:25], 0, v[130:131]
	s_add_i32 m0, s26, 0x2000
	s_nop 0
	global_load_lds_dwordx4 v[140:141], off
	s_waitcnt vmcnt(6)
	s_barrier
	v_mfma_f32_16x16x32_bf16 v[54:57], v[230:233], v[180:183], v[54:57]
	v_mfma_f32_16x16x32_bf16 v[46:49], v[238:241], v[180:183], v[46:49]
	v_mfma_f32_16x16x32_bf16 v[38:41], v[230:233], v[206:209], v[38:41]
	v_mfma_f32_16x16x32_bf16 v[30:33], v[238:241], v[206:209], v[30:33]
	v_mfma_f32_16x16x32_bf16 v[22:25], v[230:233], v[214:217], v[22:25]
	v_mfma_f32_16x16x32_bf16 v[14:17], v[238:241], v[214:217], v[14:17]
	v_mfma_f32_16x16x32_bf16 v[6:9], v[230:233], v[222:225], v[6:9]
	v_mfma_f32_16x16x32_bf16 v[2:5], v[238:241], v[222:225], v[2:5]
	v_mfma_f32_16x16x32_bf16 v[54:57], v[234:237], v[184:187], v[54:57]
	v_mfma_f32_16x16x32_bf16 v[46:49], v[242:245], v[184:187], v[46:49]
	v_mfma_f32_16x16x32_bf16 v[38:41], v[234:237], v[210:213], v[38:41]
	v_mfma_f32_16x16x32_bf16 v[30:33], v[242:245], v[210:213], v[30:33]
	v_mfma_f32_16x16x32_bf16 v[22:25], v[234:237], v[218:221], v[22:25]
	v_mfma_f32_16x16x32_bf16 v[14:17], v[242:245], v[218:221], v[14:17]
	v_mfma_f32_16x16x32_bf16 v[6:9], v[234:237], v[226:229], v[6:9]
	v_mfma_f32_16x16x32_bf16 v[2:5], v[242:245], v[226:229], v[2:5]
	s_barrier
	s_add_i32 s51, s51, 2
	s_add_u32 s40, s40, 0x100
	s_addc_u32 s41, s41, 0
	s_cmp_gt_u32 s51, 41
	s_mov_b64 s[24:25], s[22:23]
	s_cbranch_scc0 .LBB0_331
	v_lshl_or_b32 v140, s50, 8, v145
	v_lshl_add_u32 v164, s49, 8, v143
	v_ashrrev_i32_e32 v141, 31, v140
	v_ashrrev_i32_e32 v165, 31, v164
	v_lshl_add_u64 v[166:167], v[140:141], 1, s[20:21]
	v_lshlrev_b64 v[140:141], 11, v[164:165]
	v_lshl_add_u64 v[140:141], v[166:167], 0, v[140:141]
	v_pk_add_f32 v[128:129], v[128:129], 0 op_sel_hi:[1,0]
	v_pk_add_f32 v[126:127], v[126:127], 0 op_sel_hi:[1,0]
	v_pk_add_f32 v[168:169], v[124:125], 0 op_sel_hi:[1,0]
	v_pk_add_f32 v[124:125], v[122:123], 0 op_sel_hi:[1,0]
	v_cvt_pk_bf16_f32 v122, v126, v127
	v_cvt_pk_bf16_f32 v123, v128, v129
	v_pk_add_f32 v[118:119], v[118:119], 0 op_sel_hi:[1,0]
	v_cvt_pk_bf16_f32 v124, v124, v125
	v_cvt_pk_bf16_f32 v125, v168, v169
	global_store_dwordx4 v[140:141], v[122:125], off
	v_pk_add_f32 v[120:121], v[120:121], 0 op_sel_hi:[1,0]
	v_pk_add_f32 v[114:115], v[114:115], 0 op_sel_hi:[1,0]
	v_pk_add_f32 v[122:123], v[112:113], 0 op_sel_hi:[1,0]
	v_pk_add_f32 v[112:113], v[110:111], 0 op_sel_hi:[1,0]
	v_cvt_pk_bf16_f32 v110, v118, v119
	v_cvt_pk_bf16_f32 v111, v120, v121
	v_pk_add_f32 v[102:103], v[102:103], 0 op_sel_hi:[1,0]
	v_cvt_pk_bf16_f32 v112, v112, v113
	v_cvt_pk_bf16_f32 v113, v122, v123
	global_store_dwordx4 v[140:141], v[110:113], off offset:256
	v_pk_add_f32 v[104:105], v[104:105], 0 op_sel_hi:[1,0]
	v_pk_add_f32 v[98:99], v[98:99], 0 op_sel_hi:[1,0]
	v_or_b32_e32 v110, 16, v164
	v_ashrrev_i32_e32 v111, 31, v110
	v_lshlrev_b64 v[110:111], 11, v[110:111]
	v_lshl_add_u64 v[110:111], v[166:167], 0, v[110:111]
	v_pk_add_f32 v[112:113], v[116:117], 0 op_sel_hi:[1,0]
	v_pk_add_f32 v[116:117], v[108:109], 0 op_sel_hi:[1,0]
	v_pk_add_f32 v[108:109], v[106:107], 0 op_sel_hi:[1,0]
	v_cvt_pk_bf16_f32 v106, v114, v115
	v_cvt_pk_bf16_f32 v107, v112, v113
	v_pk_add_f32 v[86:87], v[86:87], 0 op_sel_hi:[1,0]
	v_cvt_pk_bf16_f32 v108, v108, v109
	v_cvt_pk_bf16_f32 v109, v116, v117
	global_store_dwordx4 v[110:111], v[106:109], off
	v_pk_add_f32 v[88:89], v[88:89], 0 op_sel_hi:[1,0]
	v_pk_add_f32 v[82:83], v[82:83], 0 op_sel_hi:[1,0]
	v_pk_add_f32 v[106:107], v[96:97], 0 op_sel_hi:[1,0]
	v_pk_add_f32 v[96:97], v[94:95], 0 op_sel_hi:[1,0]
	v_cvt_pk_bf16_f32 v94, v102, v103
	v_cvt_pk_bf16_f32 v95, v104, v105
	v_pk_add_f32 v[72:73], v[72:73], 0 op_sel_hi:[1,0]
	v_cvt_pk_bf16_f32 v96, v96, v97
	v_cvt_pk_bf16_f32 v97, v106, v107
	global_store_dwordx4 v[110:111], v[94:97], off offset:256
	v_pk_add_f32 v[70:71], v[70:71], 0 op_sel_hi:[1,0]
	v_pk_add_f32 v[62:63], v[62:63], 0 op_sel_hi:[1,0]
	v_or_b32_e32 v94, 32, v164
	v_ashrrev_i32_e32 v95, 31, v94
	v_lshlrev_b64 v[94:95], 11, v[94:95]
	v_lshl_add_u64 v[94:95], v[166:167], 0, v[94:95]
	v_pk_add_f32 v[96:97], v[100:101], 0 op_sel_hi:[1,0]
	v_pk_add_f32 v[100:101], v[92:93], 0 op_sel_hi:[1,0]
	v_pk_add_f32 v[92:93], v[90:91], 0 op_sel_hi:[1,0]
	v_cvt_pk_bf16_f32 v90, v98, v99
	v_cvt_pk_bf16_f32 v91, v96, v97
	v_pk_add_f32 v[64:65], v[64:65], 0 op_sel_hi:[1,0]
	v_cvt_pk_bf16_f32 v92, v92, v93
	v_cvt_pk_bf16_f32 v93, v100, v101
	global_store_dwordx4 v[94:95], v[90:93], off
	s_mov_b64 s[22:23], 0x40000
	v_pk_add_f32 v[56:57], v[56:57], 0 op_sel_hi:[1,0]
	v_pk_add_f32 v[90:91], v[80:81], 0 op_sel_hi:[1,0]
	v_pk_add_f32 v[80:81], v[78:79], 0 op_sel_hi:[1,0]
	v_cvt_pk_bf16_f32 v78, v86, v87
	v_cvt_pk_bf16_f32 v79, v88, v89
	v_pk_add_f32 v[54:55], v[54:55], 0 op_sel_hi:[1,0]
	v_cvt_pk_bf16_f32 v80, v80, v81
	v_cvt_pk_bf16_f32 v81, v90, v91
	global_store_dwordx4 v[94:95], v[78:81], off offset:256
	v_pk_add_f32 v[50:51], v[50:51], 0 op_sel_hi:[1,0]
	v_pk_add_f32 v[40:41], v[40:41], 0 op_sel_hi:[1,0]
	v_or_b32_e32 v78, 48, v164
	v_ashrrev_i32_e32 v79, 31, v78
	v_lshlrev_b64 v[78:79], 11, v[78:79]
	v_lshl_add_u64 v[78:79], v[166:167], 0, v[78:79]
	v_pk_add_f32 v[80:81], v[84:85], 0 op_sel_hi:[1,0]
	v_pk_add_f32 v[84:85], v[76:77], 0 op_sel_hi:[1,0]
	v_pk_add_f32 v[76:77], v[74:75], 0 op_sel_hi:[1,0]
	v_cvt_pk_bf16_f32 v74, v82, v83
	v_cvt_pk_bf16_f32 v75, v80, v81
	v_pk_add_f32 v[38:39], v[38:39], 0 op_sel_hi:[1,0]
	v_cvt_pk_bf16_f32 v76, v76, v77
	v_cvt_pk_bf16_f32 v77, v84, v85
	global_store_dwordx4 v[78:79], v[74:77], off
	v_pk_add_f32 v[34:35], v[34:35], 0 op_sel_hi:[1,0]
	v_pk_add_f32 v[24:25], v[24:25], 0 op_sel_hi:[1,0]
	v_pk_add_f32 v[74:75], v[68:69], 0 op_sel_hi:[1,0]
	v_pk_add_f32 v[68:69], v[66:67], 0 op_sel_hi:[1,0]
	v_cvt_pk_bf16_f32 v66, v70, v71
	v_cvt_pk_bf16_f32 v67, v72, v73
	v_pk_add_f32 v[22:23], v[22:23], 0 op_sel_hi:[1,0]
	v_cvt_pk_bf16_f32 v68, v68, v69
	v_cvt_pk_bf16_f32 v69, v74, v75
	global_store_dwordx4 v[78:79], v[66:69], off offset:256
	v_pk_add_f32 v[18:19], v[18:19], 0 op_sel_hi:[1,0]
	s_mov_b32 s50, s47
	v_pk_add_f32 v[68:69], v[60:61], 0 op_sel_hi:[1,0]
	v_pk_add_f32 v[60:61], v[58:59], 0 op_sel_hi:[1,0]
	v_cvt_pk_bf16_f32 v58, v62, v63
	v_add_co_u32_e32 v62, vcc, s67, v140
	v_cvt_pk_bf16_f32 v59, v64, v65
	v_cvt_pk_bf16_f32 v60, v60, v61
	v_cvt_pk_bf16_f32 v61, v68, v69
	v_lshl_add_u64 v[66:67], v[140:141], 0, s[22:23]
	s_nop 0
	v_addc_co_u32_e32 v63, vcc, 0, v141, vcc
	global_store_dwordx4 v[62:63], v[58:61], off
	s_mov_b64 s[22:23], 0x48000
	s_mov_b32 s49, s48
	v_pk_add_f32 v[58:59], v[48:49], 0 op_sel_hi:[1,0]
	v_pk_add_f32 v[48:49], v[46:47], 0 op_sel_hi:[1,0]
	v_cvt_pk_bf16_f32 v46, v54, v55
	v_cvt_pk_bf16_f32 v47, v56, v57
	s_mov_b64 s[24:25], s[2:3]
	v_cvt_pk_bf16_f32 v48, v48, v49
	v_cvt_pk_bf16_f32 v49, v58, v59
	global_store_dwordx4 v[66:67], v[46:49], off offset:256
	v_pk_add_f32 v[8:9], v[8:9], 0 op_sel_hi:[1,0]
	v_pk_add_f32 v[6:7], v[6:7], 0 op_sel_hi:[1,0]
	v_pk_add_f32 v[48:49], v[52:53], 0 op_sel_hi:[1,0]
	v_pk_add_f32 v[52:53], v[44:45], 0 op_sel_hi:[1,0]
	v_pk_add_f32 v[44:45], v[42:43], 0 op_sel_hi:[1,0]
	v_cvt_pk_bf16_f32 v42, v50, v51
	v_cvt_pk_bf16_f32 v43, v48, v49
	v_add_co_u32_e32 v48, vcc, s68, v140
	v_cvt_pk_bf16_f32 v44, v44, v45
	v_cvt_pk_bf16_f32 v45, v52, v53
	v_lshl_add_u64 v[46:47], v[140:141], 0, s[22:23]
	s_nop 0
	v_addc_co_u32_e32 v49, vcc, 0, v141, vcc
	global_store_dwordx4 v[48:49], v[42:45], off
	s_mov_b64 s[22:23], 0x50000
	s_nop 0
	v_pk_add_f32 v[42:43], v[32:33], 0 op_sel_hi:[1,0]
	v_pk_add_f32 v[32:33], v[30:31], 0 op_sel_hi:[1,0]
	v_cvt_pk_bf16_f32 v30, v38, v39
	v_cvt_pk_bf16_f32 v31, v40, v41
	s_nop 0
	v_cvt_pk_bf16_f32 v32, v32, v33
	v_cvt_pk_bf16_f32 v33, v42, v43
	global_store_dwordx4 v[46:47], v[30:33], off offset:256
	s_nop 1
	v_lshl_add_u64 v[30:31], v[140:141], 0, s[22:23]
	v_pk_add_f32 v[32:33], v[36:37], 0 op_sel_hi:[1,0]
	s_mov_b32 s22, 0x50000
	v_pk_add_f32 v[36:37], v[28:29], 0 op_sel_hi:[1,0]
	v_pk_add_f32 v[28:29], v[26:27], 0 op_sel_hi:[1,0]
	v_cvt_pk_bf16_f32 v26, v34, v35
	v_cvt_pk_bf16_f32 v27, v32, v33
	v_add_co_u32_e32 v32, vcc, s22, v140
	v_cvt_pk_bf16_f32 v28, v28, v29
	v_cvt_pk_bf16_f32 v29, v36, v37
	s_mov_b64 s[22:23], 0x58000
	s_nop 0
	v_addc_co_u32_e32 v33, vcc, 0, v141, vcc
	global_store_dwordx4 v[32:33], v[26:29], off
	s_nop 1
	v_pk_add_f32 v[26:27], v[16:17], 0 op_sel_hi:[1,0]
	v_pk_add_f32 v[16:17], v[14:15], 0 op_sel_hi:[1,0]
	v_cvt_pk_bf16_f32 v14, v22, v23
	v_cvt_pk_bf16_f32 v15, v24, v25
	s_nop 0
	v_cvt_pk_bf16_f32 v16, v16, v17
	v_cvt_pk_bf16_f32 v17, v26, v27
	global_store_dwordx4 v[30:31], v[14:17], off offset:256
	s_nop 1
	v_lshl_add_u64 v[14:15], v[140:141], 0, s[22:23]
	v_pk_add_f32 v[16:17], v[20:21], 0 op_sel_hi:[1,0]
	s_mov_b32 s22, 0x58000
	v_pk_add_f32 v[20:21], v[12:13], 0 op_sel_hi:[1,0]
	v_pk_add_f32 v[12:13], v[10:11], 0 op_sel_hi:[1,0]
	v_cvt_pk_bf16_f32 v10, v18, v19
	v_cvt_pk_bf16_f32 v11, v16, v17
	v_add_co_u32_e32 v16, vcc, s22, v140
	v_cvt_pk_bf16_f32 v12, v12, v13
	v_cvt_pk_bf16_f32 v13, v20, v21
	s_mov_b64 s[22:23], s[0:1]
	s_nop 0
	v_addc_co_u32_e32 v17, vcc, 0, v141, vcc
	global_store_dwordx4 v[16:17], v[10:13], off
	s_and_b64 vcc, exec, s[38:39]
	s_nop 0
	v_pk_add_f32 v[10:11], v[4:5], 0 op_sel_hi:[1,0]
	v_pk_add_f32 v[4:5], v[2:3], 0 op_sel_hi:[1,0]
	v_cvt_pk_bf16_f32 v2, v6, v7
	v_cvt_pk_bf16_f32 v3, v8, v9
	s_nop 0
	v_cvt_pk_bf16_f32 v4, v4, v5
	v_cvt_pk_bf16_f32 v5, v10, v11
	global_store_dwordx4 v[14:15], v[2:5], off offset:256
	s_cbranch_vccz .LBB0_320
	s_waitcnt vmcnt(16)
	s_cmpk_gt_u32 s30, 0xff
	s_cbranch_scc1 .LBB0_335
	s_barrier

.Lkprio_1:
.LBB0_360:
	s_add_u32 s44, s42, 0xfffc0080
	s_addc_u32 s45, s43, -1
	s_add_i32 s63, 0, 0x10000
	v_add_u32_e32 v0, s63, v206
	ds_read_b128 v[82:85], v0
	ds_read_b128 v[86:89], v0 offset:1024
	ds_read_b128 v[90:93], v0 offset:2048
	ds_read_b128 v[94:97], v0 offset:3072
	s_cmp_eq_u32 s62, 12
	s_cselect_b32 s47, s1, s45
	s_cselect_b32 s46, s3, s44
	s_cselect_b32 s45, s31, s61
	s_cselect_b32 s44, s35, s60
	v_lshl_add_u64 v[230:231], s[42:43], 0, v[174:175]
	s_add_i32 m0, s51, 0xc000
	ds_read_b128 v[176:179], v208
	ds_read_b128 v[180:183], v208 offset:1024
	ds_read_b128 v[184:187], v208 offset:2048
	ds_read_b128 v[210:213], v208 offset:3072
	ds_read_b128 v[214:217], v208 offset:4096
	ds_read_b128 v[218:221], v208 offset:5120
	ds_read_b128 v[222:225], v208 offset:6144
	ds_read_b128 v[226:229], v208 offset:7168
	global_load_lds_dwordx4 v[230:231], off
	v_lshl_add_u64 v[230:231], s[42:43], 0, v[172:173]
	s_add_i32 m0, s51, 0xe000
	s_nop 0
	global_load_lds_dwordx4 v[230:231], off
	s_waitcnt lgkmcnt(8)
	s_barrier
	s_waitcnt lgkmcnt(0)
	v_mfma_f32_16x16x32_bf16 v[142:145], v[82:85], v[176:179], v[142:145]
	v_mfma_f32_16x16x32_bf16 v[138:141], v[90:93], v[176:179], v[138:141]
	v_mfma_f32_16x16x32_bf16 v[126:129], v[82:85], v[184:187], v[126:129]
	v_mfma_f32_16x16x32_bf16 v[122:125], v[90:93], v[184:187], v[122:125]
	v_mfma_f32_16x16x32_bf16 v[110:113], v[82:85], v[214:217], v[110:113]
	v_mfma_f32_16x16x32_bf16 v[106:109], v[90:93], v[214:217], v[106:109]
	v_mfma_f32_16x16x32_bf16 v[78:81], v[82:85], v[222:225], v[78:81]
	v_mfma_f32_16x16x32_bf16 v[74:77], v[90:93], v[222:225], v[74:77]
	v_mfma_f32_16x16x32_bf16 v[142:145], v[86:89], v[180:183], v[142:145]
	v_mfma_f32_16x16x32_bf16 v[138:141], v[94:97], v[180:183], v[138:141]
	v_mfma_f32_16x16x32_bf16 v[126:129], v[86:89], v[210:213], v[126:129]
	v_mfma_f32_16x16x32_bf16 v[122:125], v[94:97], v[210:213], v[122:125]
	v_mfma_f32_16x16x32_bf16 v[110:113], v[86:89], v[218:221], v[110:113]
	v_mfma_f32_16x16x32_bf16 v[106:109], v[94:97], v[218:221], v[106:109]
	v_mfma_f32_16x16x32_bf16 v[78:81], v[86:89], v[226:229], v[78:81]
	v_mfma_f32_16x16x32_bf16 v[74:77], v[94:97], v[226:229], v[74:77]
	s_barrier
	s_add_i32 s66, 0, 0x14000
	s_add_i32 s63, s63, s50
	v_add_u32_e32 v0, s66, v206
	v_lshl_add_u64 v[246:247], s[44:45], 0, v[164:165]
	s_mov_b32 m0, s63
	ds_read_b128 v[230:233], v0
	ds_read_b128 v[234:237], v0 offset:1024
	ds_read_b128 v[238:241], v0 offset:2048
	ds_read_b128 v[242:245], v0 offset:3072
	global_load_lds_dwordx4 v[246:247], off
	v_lshl_add_u64 v[248:249], s[44:45], 0, v[168:169]
	s_add_i32 m0, s63, 0x2000
	s_nop 0
	global_load_lds_dwordx4 v[248:249], off
	s_barrier
	s_waitcnt lgkmcnt(0)
	v_mfma_f32_16x16x32_bf16 v[134:137], v[230:233], v[176:179], v[134:137]
	v_mfma_f32_16x16x32_bf16 v[130:133], v[238:241], v[176:179], v[130:133]
	v_mfma_f32_16x16x32_bf16 v[118:121], v[230:233], v[184:187], v[118:121]
	v_mfma_f32_16x16x32_bf16 v[114:117], v[238:241], v[184:187], v[114:117]
	v_mfma_f32_16x16x32_bf16 v[102:105], v[230:233], v[214:217], v[102:105]
	v_mfma_f32_16x16x32_bf16 v[98:101], v[238:241], v[214:217], v[98:101]
	v_mfma_f32_16x16x32_bf16 v[70:73], v[230:233], v[222:225], v[70:73]
	v_mfma_f32_16x16x32_bf16 v[66:69], v[238:241], v[222:225], v[66:69]
	v_mfma_f32_16x16x32_bf16 v[134:137], v[234:237], v[180:183], v[134:137]
	v_mfma_f32_16x16x32_bf16 v[130:133], v[242:245], v[180:183], v[130:133]
	v_mfma_f32_16x16x32_bf16 v[118:121], v[234:237], v[210:213], v[118:121]
	v_mfma_f32_16x16x32_bf16 v[114:117], v[242:245], v[210:213], v[114:117]
	v_mfma_f32_16x16x32_bf16 v[102:105], v[234:237], v[218:221], v[102:105]
	v_mfma_f32_16x16x32_bf16 v[98:101], v[242:245], v[218:221], v[98:101]
	v_mfma_f32_16x16x32_bf16 v[70:73], v[234:237], v[226:229], v[70:73]
	v_mfma_f32_16x16x32_bf16 v[66:69], v[242:245], v[226:229], v[66:69]
	s_barrier
	s_mov_b32 m0, s51
	v_lshl_add_u64 v[250:251], s[46:47], 0, v[162:163]
	ds_read_b128 v[176:179], v208 offset:16384
	ds_read_b128 v[180:183], v208 offset:17408
	ds_read_b128 v[184:187], v208 offset:18432
	ds_read_b128 v[210:213], v208 offset:19456
	ds_read_b128 v[214:217], v208 offset:20480
	ds_read_b128 v[218:221], v208 offset:21504
	ds_read_b128 v[222:225], v208 offset:22528
	ds_read_b128 v[226:229], v208 offset:23552
	global_load_lds_dwordx4 v[250:251], off
	v_lshl_add_u64 v[252:253], s[46:47], 0, v[166:167]
	s_mov_b32 m0, s52
	s_nop 0
	global_load_lds_dwordx4 v[252:253], off
	s_barrier
	s_waitcnt lgkmcnt(0)
	v_mfma_f32_16x16x32_bf16 v[62:65], v[82:85], v[176:179], v[62:65]
	v_mfma_f32_16x16x32_bf16 v[58:61], v[90:93], v[176:179], v[58:61]
	v_mfma_f32_16x16x32_bf16 v[46:49], v[82:85], v[184:187], v[46:49]
	v_mfma_f32_16x16x32_bf16 v[42:45], v[90:93], v[184:187], v[42:45]
	v_mfma_f32_16x16x32_bf16 v[30:33], v[82:85], v[214:217], v[30:33]
	v_mfma_f32_16x16x32_bf16 v[26:29], v[90:93], v[214:217], v[26:29]
	v_mfma_f32_16x16x32_bf16 v[14:17], v[82:85], v[222:225], v[14:17]
	v_mfma_f32_16x16x32_bf16 v[10:13], v[90:93], v[222:225], v[10:13]
	v_mfma_f32_16x16x32_bf16 v[62:65], v[86:89], v[180:183], v[62:65]
	v_mfma_f32_16x16x32_bf16 v[58:61], v[94:97], v[180:183], v[58:61]
	v_mfma_f32_16x16x32_bf16 v[46:49], v[86:89], v[210:213], v[46:49]
	v_mfma_f32_16x16x32_bf16 v[42:45], v[94:97], v[210:213], v[42:45]
	v_mfma_f32_16x16x32_bf16 v[30:33], v[86:89], v[218:221], v[30:33]
	v_mfma_f32_16x16x32_bf16 v[26:29], v[94:97], v[218:221], v[26:29]
	v_mfma_f32_16x16x32_bf16 v[14:17], v[86:89], v[226:229], v[14:17]
	v_mfma_f32_16x16x32_bf16 v[10:13], v[94:97], v[226:229], v[10:13]
	s_barrier
	s_add_u32 s64, s44, 0x40000
	s_addc_u32 s65, s45, 0
	s_add_i32 s63, s66, s50
	v_lshl_add_u64 v[82:83], s[64:65], 0, v[164:165]
	s_mov_b32 m0, s63
	s_nop 0
	global_load_lds_dwordx4 v[82:83], off
	v_lshl_add_u64 v[82:83], s[64:65], 0, v[168:169]
	s_add_i32 m0, s63, 0x2000
	s_nop 0
	global_load_lds_dwordx4 v[82:83], off
	s_waitcnt vmcnt(6)
	s_barrier
	v_mfma_f32_16x16x32_bf16 v[54:57], v[230:233], v[176:179], v[54:57]
	v_mfma_f32_16x16x32_bf16 v[50:53], v[238:241], v[176:179], v[50:53]
	v_mfma_f32_16x16x32_bf16 v[38:41], v[230:233], v[184:187], v[38:41]
	v_mfma_f32_16x16x32_bf16 v[34:37], v[238:241], v[184:187], v[34:37]
	v_mfma_f32_16x16x32_bf16 v[22:25], v[230:233], v[214:217], v[22:25]
	v_mfma_f32_16x16x32_bf16 v[18:21], v[238:241], v[214:217], v[18:21]
	v_mfma_f32_16x16x32_bf16 v[6:9], v[230:233], v[222:225], v[6:9]
	v_mfma_f32_16x16x32_bf16 v[2:5], v[238:241], v[222:225], v[2:5]
	v_mfma_f32_16x16x32_bf16 v[54:57], v[234:237], v[180:183], v[54:57]
	v_mfma_f32_16x16x32_bf16 v[50:53], v[242:245], v[180:183], v[50:53]
	v_mfma_f32_16x16x32_bf16 v[38:41], v[234:237], v[210:213], v[38:41]
	v_mfma_f32_16x16x32_bf16 v[34:37], v[242:245], v[210:213], v[34:37]
	v_mfma_f32_16x16x32_bf16 v[22:25], v[234:237], v[218:221], v[22:25]
	v_mfma_f32_16x16x32_bf16 v[18:21], v[242:245], v[218:221], v[18:21]
	v_mfma_f32_16x16x32_bf16 v[6:9], v[234:237], v[226:229], v[6:9]
	v_mfma_f32_16x16x32_bf16 v[2:5], v[242:245], v[226:229], v[2:5]
	s_barrier
	s_add_i32 s63, 0, 0x18000
	v_add_u32_e32 v0, s63, v206
	ds_read_b128 v[82:85], v0
	ds_read_b128 v[86:89], v0 offset:1024
	ds_read_b128 v[90:93], v0 offset:2048
	ds_read_b128 v[94:97], v0 offset:3072
	s_add_u32 s46, s46, 0x40000
	s_addc_u32 s47, s47, 0
	s_mov_b32 m0, s53
	v_lshl_add_u64 v[230:231], s[46:47], 0, v[162:163]
	ds_read_b128 v[176:179], v208 offset:32768
	ds_read_b128 v[180:183], v208 offset:33792
	ds_read_b128 v[184:187], v208 offset:34816
	ds_read_b128 v[210:213], v208 offset:35840
	ds_read_b128 v[214:217], v208 offset:36864
	ds_read_b128 v[218:221], v208 offset:37888
	ds_read_b128 v[222:225], v208 offset:38912
	ds_read_b128 v[226:229], v208 offset:39936
	global_load_lds_dwordx4 v[230:231], off
	v_lshl_add_u64 v[230:231], s[46:47], 0, v[166:167]
	s_mov_b32 m0, s54
	s_nop 0
	global_load_lds_dwordx4 v[230:231], off
	s_waitcnt lgkmcnt(8)
	s_barrier
	s_waitcnt lgkmcnt(0)
	v_mfma_f32_16x16x32_bf16 v[142:145], v[82:85], v[176:179], v[142:145]
	v_mfma_f32_16x16x32_bf16 v[138:141], v[90:93], v[176:179], v[138:141]
	v_mfma_f32_16x16x32_bf16 v[126:129], v[82:85], v[184:187], v[126:129]
	v_mfma_f32_16x16x32_bf16 v[122:125], v[90:93], v[184:187], v[122:125]
	v_mfma_f32_16x16x32_bf16 v[110:113], v[82:85], v[214:217], v[110:113]
	v_mfma_f32_16x16x32_bf16 v[106:109], v[90:93], v[214:217], v[106:109]
	v_mfma_f32_16x16x32_bf16 v[78:81], v[82:85], v[222:225], v[78:81]
	v_mfma_f32_16x16x32_bf16 v[74:77], v[90:93], v[222:225], v[74:77]
	v_mfma_f32_16x16x32_bf16 v[142:145], v[86:89], v[180:183], v[142:145]
	v_mfma_f32_16x16x32_bf16 v[138:141], v[94:97], v[180:183], v[138:141]
	v_mfma_f32_16x16x32_bf16 v[126:129], v[86:89], v[210:213], v[126:129]
	v_mfma_f32_16x16x32_bf16 v[122:125], v[94:97], v[210:213], v[122:125]
	v_mfma_f32_16x16x32_bf16 v[110:113], v[86:89], v[218:221], v[110:113]
	v_mfma_f32_16x16x32_bf16 v[106:109], v[94:97], v[218:221], v[106:109]
	v_mfma_f32_16x16x32_bf16 v[78:81], v[86:89], v[226:229], v[78:81]
	v_mfma_f32_16x16x32_bf16 v[74:77], v[94:97], v[226:229], v[74:77]
	s_barrier
	s_add_i32 s46, 0, 0x1c000
	s_add_i32 s47, s63, s50
	v_add_u32_e32 v0, s46, v206
	v_lshl_add_u64 v[246:247], v[246:247], 0, s[94:95]
	s_mov_b32 m0, s47
	ds_read_b128 v[230:233], v0
	ds_read_b128 v[234:237], v0 offset:1024
	ds_read_b128 v[238:241], v0 offset:2048
	ds_read_b128 v[242:245], v0 offset:3072
	global_load_lds_dwordx4 v[246:247], off
	v_lshl_add_u64 v[246:247], v[248:249], 0, s[94:95]
	s_add_i32 m0, s47, 0x2000
	s_nop 0
	global_load_lds_dwordx4 v[246:247], off
	s_barrier
	s_waitcnt lgkmcnt(0)
	v_mfma_f32_16x16x32_bf16 v[134:137], v[230:233], v[176:179], v[134:137]
	v_mfma_f32_16x16x32_bf16 v[130:133], v[238:241], v[176:179], v[130:133]
	v_mfma_f32_16x16x32_bf16 v[118:121], v[230:233], v[184:187], v[118:121]
	v_mfma_f32_16x16x32_bf16 v[114:117], v[238:241], v[184:187], v[114:117]
	v_mfma_f32_16x16x32_bf16 v[102:105], v[230:233], v[214:217], v[102:105]
	v_mfma_f32_16x16x32_bf16 v[98:101], v[238:241], v[214:217], v[98:101]
	v_mfma_f32_16x16x32_bf16 v[70:73], v[230:233], v[222:225], v[70:73]
	v_mfma_f32_16x16x32_bf16 v[66:69], v[238:241], v[222:225], v[66:69]
	v_mfma_f32_16x16x32_bf16 v[134:137], v[234:237], v[180:183], v[134:137]
	v_mfma_f32_16x16x32_bf16 v[130:133], v[242:245], v[180:183], v[130:133]
	v_mfma_f32_16x16x32_bf16 v[118:121], v[234:237], v[210:213], v[118:121]
	v_mfma_f32_16x16x32_bf16 v[114:117], v[242:245], v[210:213], v[114:117]
	v_mfma_f32_16x16x32_bf16 v[102:105], v[234:237], v[218:221], v[102:105]
	v_mfma_f32_16x16x32_bf16 v[98:101], v[242:245], v[218:221], v[98:101]
	v_mfma_f32_16x16x32_bf16 v[70:73], v[234:237], v[226:229], v[70:73]
	v_mfma_f32_16x16x32_bf16 v[66:69], v[242:245], v[226:229], v[66:69]
	s_barrier
	s_mov_b32 m0, s56
	v_lshl_add_u64 v[246:247], v[250:251], 0, s[94:95]
	ds_read_b128 v[176:179], v208 offset:49152
	ds_read_b128 v[180:183], v208 offset:50176
	ds_read_b128 v[184:187], v208 offset:51200
	ds_read_b128 v[210:213], v208 offset:52224
	ds_read_b128 v[214:217], v208 offset:53248
	ds_read_b128 v[218:221], v208 offset:54272
	ds_read_b128 v[222:225], v208 offset:55296
	ds_read_b128 v[226:229], v208 offset:56320
	global_load_lds_dwordx4 v[246:247], off
	v_lshl_add_u64 v[246:247], v[252:253], 0, s[94:95]
	s_mov_b32 m0, s57
	s_nop 0
	global_load_lds_dwordx4 v[246:247], off
	s_barrier
	s_waitcnt lgkmcnt(0)
	v_mfma_f32_16x16x32_bf16 v[62:65], v[82:85], v[176:179], v[62:65]
	v_mfma_f32_16x16x32_bf16 v[58:61], v[90:93], v[176:179], v[58:61]
	v_mfma_f32_16x16x32_bf16 v[46:49], v[82:85], v[184:187], v[46:49]
	v_mfma_f32_16x16x32_bf16 v[42:45], v[90:93], v[184:187], v[42:45]
	v_mfma_f32_16x16x32_bf16 v[30:33], v[82:85], v[214:217], v[30:33]
	v_mfma_f32_16x16x32_bf16 v[26:29], v[90:93], v[214:217], v[26:29]
	v_mfma_f32_16x16x32_bf16 v[14:17], v[82:85], v[222:225], v[14:17]
	v_mfma_f32_16x16x32_bf16 v[10:13], v[90:93], v[222:225], v[10:13]
	v_mfma_f32_16x16x32_bf16 v[62:65], v[86:89], v[180:183], v[62:65]
	v_mfma_f32_16x16x32_bf16 v[58:61], v[94:97], v[180:183], v[58:61]
	v_mfma_f32_16x16x32_bf16 v[46:49], v[86:89], v[210:213], v[46:49]
	v_mfma_f32_16x16x32_bf16 v[42:45], v[94:97], v[210:213], v[42:45]
	v_mfma_f32_16x16x32_bf16 v[30:33], v[86:89], v[218:221], v[30:33]
	v_mfma_f32_16x16x32_bf16 v[26:29], v[94:97], v[218:221], v[26:29]
	v_mfma_f32_16x16x32_bf16 v[14:17], v[86:89], v[226:229], v[14:17]
	v_mfma_f32_16x16x32_bf16 v[10:13], v[94:97], v[226:229], v[10:13]
	s_barrier
	s_add_u32 s44, s44, 0x40080
	s_addc_u32 s45, s45, 0
	s_add_i32 s46, s46, s50
	v_lshl_add_u64 v[82:83], s[44:45], 0, v[164:165]
	s_mov_b32 m0, s46
	s_nop 0
	global_load_lds_dwordx4 v[82:83], off
	v_lshl_add_u64 v[82:83], s[44:45], 0, v[168:169]
	s_add_i32 m0, s46, 0x2000
	s_nop 0
	global_load_lds_dwordx4 v[82:83], off
	s_waitcnt vmcnt(6)
	s_barrier
	v_mfma_f32_16x16x32_bf16 v[54:57], v[230:233], v[176:179], v[54:57]
	v_mfma_f32_16x16x32_bf16 v[50:53], v[238:241], v[176:179], v[50:53]
	v_mfma_f32_16x16x32_bf16 v[38:41], v[230:233], v[184:187], v[38:41]
	v_mfma_f32_16x16x32_bf16 v[34:37], v[238:241], v[184:187], v[34:37]
	v_mfma_f32_16x16x32_bf16 v[22:25], v[230:233], v[214:217], v[22:25]
	v_mfma_f32_16x16x32_bf16 v[18:21], v[238:241], v[214:217], v[18:21]
	v_mfma_f32_16x16x32_bf16 v[6:9], v[230:233], v[222:225], v[6:9]
	v_mfma_f32_16x16x32_bf16 v[2:5], v[238:241], v[222:225], v[2:5]
	v_mfma_f32_16x16x32_bf16 v[54:57], v[234:237], v[180:183], v[54:57]
	v_mfma_f32_16x16x32_bf16 v[50:53], v[242:245], v[180:183], v[50:53]
	v_mfma_f32_16x16x32_bf16 v[38:41], v[234:237], v[210:213], v[38:41]
	v_mfma_f32_16x16x32_bf16 v[34:37], v[242:245], v[210:213], v[34:37]
	v_mfma_f32_16x16x32_bf16 v[22:25], v[234:237], v[218:221], v[22:25]
	v_mfma_f32_16x16x32_bf16 v[18:21], v[242:245], v[218:221], v[18:21]
	v_mfma_f32_16x16x32_bf16 v[6:9], v[234:237], v[226:229], v[6:9]
	v_mfma_f32_16x16x32_bf16 v[2:5], v[242:245], v[226:229], v[2:5]
	s_barrier
	s_add_i32 s62, s62, 2
	s_add_u32 s60, s60, 0x100
	s_addc_u32 s61, s61, 0
	s_add_u32 s42, s42, 0x100
	s_addc_u32 s43, s43, 0
	s_cmp_gt_u32 s62, 13
	s_cbranch_scc0 .LBB0_360
	v_lshl_or_b32 v180, s0, 8, v207
	v_ashrrev_i32_e32 v181, 31, v180
	v_mov_b32_e32 v86, 0
	v_cndmask_b32_e64 v0, 0, 1, s[26:27]
	v_lshl_add_u64 v[176:177], v[180:181], 2, s[22:23]
	v_cmp_ne_u32_e64 s[0:1], 1, v0
	s_andn2_b64 vcc, exec, s[26:27]
	v_mov_b32_e32 v94, 0
	v_mov_b32_e32 v95, v86
	v_mov_b32_e32 v96, 0
	v_mov_b32_e32 v97, 0
	s_cbranch_vccnz .LBB0_363
	global_load_dwordx4 v[94:97], v[176:177], off

.Lkprio_0:
.LBB0_586:
	s_add_u32 s22, s20, 0xfffc0080
	s_addc_u32 s23, s21, -1
	s_add_i32 s48, 0, 0x10000
	v_add_u32_e32 v140, s48, v143
	ds_read_b128 v[162:165], v140
	ds_read_b128 v[166:169], v140 offset:1024
	ds_read_b128 v[170:173], v140 offset:2048
	ds_read_b128 v[174:177], v140 offset:3072
	s_cmp_eq_u32 s47, 12
	s_cselect_b32 s25, s9, s23
	s_cselect_b32 s24, s43, s22
	s_cselect_b32 s23, s1, s46
	s_cselect_b32 s22, s44, s45
	v_lshl_add_u64 v[140:141], s[20:21], 0, v[136:137]
	s_add_i32 m0, s3, 0xc000
	ds_read_b128 v[178:181], v145
	ds_read_b128 v[182:185], v145 offset:1024
	ds_read_b128 v[206:209], v145 offset:2048
	ds_read_b128 v[210:213], v145 offset:3072
	ds_read_b128 v[214:217], v145 offset:4096
	ds_read_b128 v[218:221], v145 offset:5120
	ds_read_b128 v[222:225], v145 offset:6144
	ds_read_b128 v[226:229], v145 offset:7168
	global_load_lds_dwordx4 v[140:141], off
	v_lshl_add_u64 v[140:141], s[20:21], 0, v[138:139]
	s_add_i32 m0, s3, 0xe000
	s_nop 0
	global_load_lds_dwordx4 v[140:141], off
	s_waitcnt lgkmcnt(8)
	s_barrier
	s_waitcnt lgkmcnt(0)
	v_mfma_f32_16x16x32_bf16 v[122:125], v[162:165], v[178:181], v[122:125]
	v_mfma_f32_16x16x32_bf16 v[114:117], v[170:173], v[178:181], v[114:117]
	v_mfma_f32_16x16x32_bf16 v[106:109], v[162:165], v[206:209], v[106:109]
	v_mfma_f32_16x16x32_bf16 v[98:101], v[170:173], v[206:209], v[98:101]
	v_mfma_f32_16x16x32_bf16 v[90:93], v[162:165], v[214:217], v[90:93]
	v_mfma_f32_16x16x32_bf16 v[82:85], v[170:173], v[214:217], v[82:85]
	v_mfma_f32_16x16x32_bf16 v[74:77], v[162:165], v[222:225], v[74:77]
	v_mfma_f32_16x16x32_bf16 v[66:69], v[170:173], v[222:225], v[66:69]
	v_mfma_f32_16x16x32_bf16 v[122:125], v[166:169], v[182:185], v[122:125]
	v_mfma_f32_16x16x32_bf16 v[114:117], v[174:177], v[182:185], v[114:117]
	v_mfma_f32_16x16x32_bf16 v[106:109], v[166:169], v[210:213], v[106:109]
	v_mfma_f32_16x16x32_bf16 v[98:101], v[174:177], v[210:213], v[98:101]
	v_mfma_f32_16x16x32_bf16 v[90:93], v[166:169], v[218:221], v[90:93]
	v_mfma_f32_16x16x32_bf16 v[82:85], v[174:177], v[218:221], v[82:85]
	v_mfma_f32_16x16x32_bf16 v[74:77], v[166:169], v[226:229], v[74:77]
	v_mfma_f32_16x16x32_bf16 v[66:69], v[174:177], v[226:229], v[66:69]
	s_barrier
	s_add_i32 s50, 0, 0x14000
	v_add_u32_e32 v140, s50, v143
	s_add_i32 s48, s48, s29
	ds_read_b128 v[230:233], v140
	ds_read_b128 v[234:237], v140 offset:1024
	ds_read_b128 v[238:241], v140 offset:2048
	ds_read_b128 v[242:245], v140 offset:3072
	v_lshl_add_u64 v[140:141], s[22:23], 0, v[0:1]
	s_mov_b32 m0, s48
	v_lshl_add_u64 v[186:187], s[22:23], 0, v[130:131]
	global_load_lds_dwordx4 v[140:141], off
	s_add_i32 m0, s48, 0x2000
	s_nop 0
	global_load_lds_dwordx4 v[186:187], off
	s_barrier
	s_waitcnt lgkmcnt(0)
	v_mfma_f32_16x16x32_bf16 v[126:129], v[230:233], v[178:181], v[126:129]
	v_mfma_f32_16x16x32_bf16 v[118:121], v[238:241], v[178:181], v[118:121]
	v_mfma_f32_16x16x32_bf16 v[110:113], v[230:233], v[206:209], v[110:113]
	v_mfma_f32_16x16x32_bf16 v[102:105], v[238:241], v[206:209], v[102:105]
	v_mfma_f32_16x16x32_bf16 v[94:97], v[230:233], v[214:217], v[94:97]
	v_mfma_f32_16x16x32_bf16 v[86:89], v[238:241], v[214:217], v[86:89]
	v_mfma_f32_16x16x32_bf16 v[78:81], v[230:233], v[222:225], v[78:81]
	v_mfma_f32_16x16x32_bf16 v[70:73], v[238:241], v[222:225], v[70:73]
	v_mfma_f32_16x16x32_bf16 v[126:129], v[234:237], v[182:185], v[126:129]
	v_mfma_f32_16x16x32_bf16 v[118:121], v[242:245], v[182:185], v[118:121]
	v_mfma_f32_16x16x32_bf16 v[110:113], v[234:237], v[210:213], v[110:113]
	v_mfma_f32_16x16x32_bf16 v[102:105], v[242:245], v[210:213], v[102:105]
	v_mfma_f32_16x16x32_bf16 v[94:97], v[234:237], v[218:221], v[94:97]
	v_mfma_f32_16x16x32_bf16 v[86:89], v[242:245], v[218:221], v[86:89]
	v_mfma_f32_16x16x32_bf16 v[78:81], v[234:237], v[226:229], v[78:81]
	v_mfma_f32_16x16x32_bf16 v[70:73], v[242:245], v[226:229], v[70:73]
	s_barrier
	s_mov_b32 m0, s3
	v_lshl_add_u64 v[246:247], s[24:25], 0, v[134:135]
	ds_read_b128 v[178:181], v145 offset:16384
	ds_read_b128 v[182:185], v145 offset:17408
	ds_read_b128 v[206:209], v145 offset:18432
	ds_read_b128 v[210:213], v145 offset:19456
	ds_read_b128 v[214:217], v145 offset:20480
	ds_read_b128 v[218:221], v145 offset:21504
	ds_read_b128 v[222:225], v145 offset:22528
	ds_read_b128 v[226:229], v145 offset:23552
	global_load_lds_dwordx4 v[246:247], off
	v_lshl_add_u64 v[248:249], s[24:25], 0, v[132:133]
	s_mov_b32 m0, s31
	s_nop 0
	global_load_lds_dwordx4 v[248:249], off
	s_barrier
	s_waitcnt lgkmcnt(0)
	v_mfma_f32_16x16x32_bf16 v[58:61], v[162:165], v[178:181], v[58:61]
	v_mfma_f32_16x16x32_bf16 v[50:53], v[170:173], v[178:181], v[50:53]
	v_mfma_f32_16x16x32_bf16 v[42:45], v[162:165], v[206:209], v[42:45]
	v_mfma_f32_16x16x32_bf16 v[34:37], v[170:173], v[206:209], v[34:37]
	v_mfma_f32_16x16x32_bf16 v[26:29], v[162:165], v[214:217], v[26:29]
	v_mfma_f32_16x16x32_bf16 v[18:21], v[170:173], v[214:217], v[18:21]
	v_mfma_f32_16x16x32_bf16 v[10:13], v[162:165], v[222:225], v[10:13]
	v_mfma_f32_16x16x32_bf16 v[6:9], v[170:173], v[222:225], v[6:9]
	v_mfma_f32_16x16x32_bf16 v[58:61], v[166:169], v[182:185], v[58:61]
	v_mfma_f32_16x16x32_bf16 v[50:53], v[174:177], v[182:185], v[50:53]
	v_mfma_f32_16x16x32_bf16 v[42:45], v[166:169], v[210:213], v[42:45]
	v_mfma_f32_16x16x32_bf16 v[34:37], v[174:177], v[210:213], v[34:37]
	v_mfma_f32_16x16x32_bf16 v[26:29], v[166:169], v[218:221], v[26:29]
	v_mfma_f32_16x16x32_bf16 v[18:21], v[174:177], v[218:221], v[18:21]
	v_mfma_f32_16x16x32_bf16 v[10:13], v[166:169], v[226:229], v[10:13]
	v_mfma_f32_16x16x32_bf16 v[6:9], v[174:177], v[226:229], v[6:9]
	s_barrier
	s_add_u32 s48, s22, 0x40000
	s_addc_u32 s49, s23, 0
	s_add_i32 s50, s50, s29
	v_lshl_add_u64 v[162:163], s[48:49], 0, v[0:1]
	s_mov_b32 m0, s50
	s_nop 0
	global_load_lds_dwordx4 v[162:163], off
	v_lshl_add_u64 v[162:163], s[48:49], 0, v[130:131]
	s_add_i32 m0, s50, 0x2000
	s_nop 0
	global_load_lds_dwordx4 v[162:163], off
	s_waitcnt vmcnt(6)
	s_barrier
	v_mfma_f32_16x16x32_bf16 v[62:65], v[230:233], v[178:181], v[62:65]
	v_mfma_f32_16x16x32_bf16 v[54:57], v[238:241], v[178:181], v[54:57]
	v_mfma_f32_16x16x32_bf16 v[46:49], v[230:233], v[206:209], v[46:49]
	v_mfma_f32_16x16x32_bf16 v[38:41], v[238:241], v[206:209], v[38:41]
	v_mfma_f32_16x16x32_bf16 v[30:33], v[230:233], v[214:217], v[30:33]
	v_mfma_f32_16x16x32_bf16 v[22:25], v[238:241], v[214:217], v[22:25]
	v_mfma_f32_16x16x32_bf16 v[14:17], v[230:233], v[222:225], v[14:17]
	v_mfma_f32_16x16x32_bf16 v[2:5], v[238:241], v[222:225], v[2:5]
	v_mfma_f32_16x16x32_bf16 v[62:65], v[234:237], v[182:185], v[62:65]
	v_mfma_f32_16x16x32_bf16 v[54:57], v[242:245], v[182:185], v[54:57]
	v_mfma_f32_16x16x32_bf16 v[46:49], v[234:237], v[210:213], v[46:49]
	v_mfma_f32_16x16x32_bf16 v[38:41], v[242:245], v[210:213], v[38:41]
	v_mfma_f32_16x16x32_bf16 v[30:33], v[234:237], v[218:221], v[30:33]
	v_mfma_f32_16x16x32_bf16 v[22:25], v[242:245], v[218:221], v[22:25]
	v_mfma_f32_16x16x32_bf16 v[14:17], v[234:237], v[226:229], v[14:17]
	v_mfma_f32_16x16x32_bf16 v[2:5], v[242:245], v[226:229], v[2:5]
	s_barrier
	s_add_i32 s48, 0, 0x18000
	v_add_u32_e32 v174, s48, v143
	ds_read_b128 v[162:165], v174
	ds_read_b128 v[166:169], v174 offset:1024
	ds_read_b128 v[170:173], v174 offset:2048
	ds_read_b128 v[174:177], v174 offset:3072
	s_add_u32 s24, s24, 0x40000
	s_addc_u32 s25, s25, 0
	s_mov_b32 m0, s34
	v_lshl_add_u64 v[230:231], s[24:25], 0, v[134:135]
	ds_read_b128 v[178:181], v145 offset:32768
	ds_read_b128 v[182:185], v145 offset:33792
	ds_read_b128 v[206:209], v145 offset:34816
	ds_read_b128 v[210:213], v145 offset:35840
	ds_read_b128 v[214:217], v145 offset:36864
	ds_read_b128 v[218:221], v145 offset:37888
	ds_read_b128 v[222:225], v145 offset:38912
	ds_read_b128 v[226:229], v145 offset:39936
	global_load_lds_dwordx4 v[230:231], off
	v_lshl_add_u64 v[230:231], s[24:25], 0, v[132:133]
	s_mov_b32 m0, s35
	s_nop 0
	global_load_lds_dwordx4 v[230:231], off
	s_waitcnt lgkmcnt(8)
	s_barrier
	s_waitcnt lgkmcnt(0)
	v_mfma_f32_16x16x32_bf16 v[122:125], v[162:165], v[178:181], v[122:125]
	v_mfma_f32_16x16x32_bf16 v[114:117], v[170:173], v[178:181], v[114:117]
	v_mfma_f32_16x16x32_bf16 v[106:109], v[162:165], v[206:209], v[106:109]
	v_mfma_f32_16x16x32_bf16 v[98:101], v[170:173], v[206:209], v[98:101]
	v_mfma_f32_16x16x32_bf16 v[90:93], v[162:165], v[214:217], v[90:93]
	v_mfma_f32_16x16x32_bf16 v[82:85], v[170:173], v[214:217], v[82:85]
	v_mfma_f32_16x16x32_bf16 v[74:77], v[162:165], v[222:225], v[74:77]
	v_mfma_f32_16x16x32_bf16 v[66:69], v[170:173], v[222:225], v[66:69]
	v_mfma_f32_16x16x32_bf16 v[122:125], v[166:169], v[182:185], v[122:125]
	v_mfma_f32_16x16x32_bf16 v[114:117], v[174:177], v[182:185], v[114:117]
	v_mfma_f32_16x16x32_bf16 v[106:109], v[166:169], v[210:213], v[106:109]
	v_mfma_f32_16x16x32_bf16 v[98:101], v[174:177], v[210:213], v[98:101]
	v_mfma_f32_16x16x32_bf16 v[90:93], v[166:169], v[218:221], v[90:93]
	v_mfma_f32_16x16x32_bf16 v[82:85], v[174:177], v[218:221], v[82:85]
	v_mfma_f32_16x16x32_bf16 v[74:77], v[166:169], v[226:229], v[74:77]
	v_mfma_f32_16x16x32_bf16 v[66:69], v[174:177], v[226:229], v[66:69]
	s_barrier
	s_add_i32 s24, 0, 0x1c000
	s_add_i32 s25, s48, s29
	v_add_u32_e32 v205, s24, v143
	v_lshl_add_u64 v[140:141], v[140:141], 0, s[94:95]
	s_mov_b32 m0, s25
	ds_read_b128 v[230:233], v205
	ds_read_b128 v[234:237], v205 offset:1024
	ds_read_b128 v[238:241], v205 offset:2048
	ds_read_b128 v[242:245], v205 offset:3072
	global_load_lds_dwordx4 v[140:141], off
	v_lshl_add_u64 v[140:141], v[186:187], 0, s[94:95]
	s_add_i32 m0, s25, 0x2000
	s_nop 0
	global_load_lds_dwordx4 v[140:141], off
	s_barrier
	s_waitcnt lgkmcnt(0)
	v_mfma_f32_16x16x32_bf16 v[126:129], v[230:233], v[178:181], v[126:129]
	v_mfma_f32_16x16x32_bf16 v[118:121], v[238:241], v[178:181], v[118:121]
	v_mfma_f32_16x16x32_bf16 v[110:113], v[230:233], v[206:209], v[110:113]
	v_mfma_f32_16x16x32_bf16 v[102:105], v[238:241], v[206:209], v[102:105]
	v_mfma_f32_16x16x32_bf16 v[94:97], v[230:233], v[214:217], v[94:97]
	v_mfma_f32_16x16x32_bf16 v[86:89], v[238:241], v[214:217], v[86:89]
	v_mfma_f32_16x16x32_bf16 v[78:81], v[230:233], v[222:225], v[78:81]
	v_mfma_f32_16x16x32_bf16 v[70:73], v[238:241], v[222:225], v[70:73]
	v_mfma_f32_16x16x32_bf16 v[126:129], v[234:237], v[182:185], v[126:129]
	v_mfma_f32_16x16x32_bf16 v[118:121], v[242:245], v[182:185], v[118:121]
	v_mfma_f32_16x16x32_bf16 v[110:113], v[234:237], v[210:213], v[110:113]
	v_mfma_f32_16x16x32_bf16 v[102:105], v[242:245], v[210:213], v[102:105]
	v_mfma_f32_16x16x32_bf16 v[94:97], v[234:237], v[218:221], v[94:97]
	v_mfma_f32_16x16x32_bf16 v[86:89], v[242:245], v[218:221], v[86:89]
	v_mfma_f32_16x16x32_bf16 v[78:81], v[234:237], v[226:229], v[78:81]
	v_mfma_f32_16x16x32_bf16 v[70:73], v[242:245], v[226:229], v[70:73]
	s_barrier
	s_mov_b32 m0, s37
	v_lshl_add_u64 v[140:141], v[246:247], 0, s[94:95]
	ds_read_b128 v[178:181], v145 offset:49152
	ds_read_b128 v[182:185], v145 offset:50176
	ds_read_b128 v[206:209], v145 offset:51200
	ds_read_b128 v[210:213], v145 offset:52224
	ds_read_b128 v[214:217], v145 offset:53248
	ds_read_b128 v[218:221], v145 offset:54272
	ds_read_b128 v[222:225], v145 offset:55296
	ds_read_b128 v[226:229], v145 offset:56320
	global_load_lds_dwordx4 v[140:141], off
	v_lshl_add_u64 v[140:141], v[248:249], 0, s[94:95]
	s_mov_b32 m0, s40
	s_nop 0
	global_load_lds_dwordx4 v[140:141], off
	s_barrier
	s_waitcnt lgkmcnt(0)
	v_mfma_f32_16x16x32_bf16 v[58:61], v[162:165], v[178:181], v[58:61]
	v_mfma_f32_16x16x32_bf16 v[50:53], v[170:173], v[178:181], v[50:53]
	v_mfma_f32_16x16x32_bf16 v[42:45], v[162:165], v[206:209], v[42:45]
	v_mfma_f32_16x16x32_bf16 v[34:37], v[170:173], v[206:209], v[34:37]
	v_mfma_f32_16x16x32_bf16 v[26:29], v[162:165], v[214:217], v[26:29]
	v_mfma_f32_16x16x32_bf16 v[18:21], v[170:173], v[214:217], v[18:21]
	v_mfma_f32_16x16x32_bf16 v[10:13], v[162:165], v[222:225], v[10:13]
	v_mfma_f32_16x16x32_bf16 v[6:9], v[170:173], v[222:225], v[6:9]
	v_mfma_f32_16x16x32_bf16 v[58:61], v[166:169], v[182:185], v[58:61]
	v_mfma_f32_16x16x32_bf16 v[50:53], v[174:177], v[182:185], v[50:53]
	v_mfma_f32_16x16x32_bf16 v[42:45], v[166:169], v[210:213], v[42:45]
	v_mfma_f32_16x16x32_bf16 v[34:37], v[174:177], v[210:213], v[34:37]
	v_mfma_f32_16x16x32_bf16 v[26:29], v[166:169], v[218:221], v[26:29]
	v_mfma_f32_16x16x32_bf16 v[18:21], v[174:177], v[218:221], v[18:21]
	v_mfma_f32_16x16x32_bf16 v[10:13], v[166:169], v[226:229], v[10:13]
	v_mfma_f32_16x16x32_bf16 v[6:9], v[174:177], v[226:229], v[6:9]
	s_barrier
	s_add_u32 s22, s22, 0x40080
	s_addc_u32 s23, s23, 0
	s_add_i32 s24, s24, s29
	v_lshl_add_u64 v[140:141], s[22:23], 0, v[0:1]
	s_mov_b32 m0, s24
	s_nop 0
	global_load_lds_dwordx4 v[140:141], off
	v_lshl_add_u64 v[140:141], s[22:23], 0, v[130:131]
	s_add_i32 m0, s24, 0x2000
	s_nop 0
	global_load_lds_dwordx4 v[140:141], off
	s_waitcnt vmcnt(6)
	s_barrier
	v_mfma_f32_16x16x32_bf16 v[62:65], v[230:233], v[178:181], v[62:65]
	v_mfma_f32_16x16x32_bf16 v[54:57], v[238:241], v[178:181], v[54:57]
	v_mfma_f32_16x16x32_bf16 v[46:49], v[230:233], v[206:209], v[46:49]
	v_mfma_f32_16x16x32_bf16 v[38:41], v[238:241], v[206:209], v[38:41]
	v_mfma_f32_16x16x32_bf16 v[30:33], v[230:233], v[214:217], v[30:33]
	v_mfma_f32_16x16x32_bf16 v[22:25], v[238:241], v[214:217], v[22:25]
	v_mfma_f32_16x16x32_bf16 v[14:17], v[230:233], v[222:225], v[14:17]
	v_mfma_f32_16x16x32_bf16 v[2:5], v[238:241], v[222:225], v[2:5]
	v_mfma_f32_16x16x32_bf16 v[62:65], v[234:237], v[182:185], v[62:65]
	v_mfma_f32_16x16x32_bf16 v[54:57], v[242:245], v[182:185], v[54:57]
	v_mfma_f32_16x16x32_bf16 v[46:49], v[234:237], v[210:213], v[46:49]
	v_mfma_f32_16x16x32_bf16 v[38:41], v[242:245], v[210:213], v[38:41]
	v_mfma_f32_16x16x32_bf16 v[30:33], v[234:237], v[218:221], v[30:33]
	v_mfma_f32_16x16x32_bf16 v[22:25], v[242:245], v[218:221], v[22:25]
	v_mfma_f32_16x16x32_bf16 v[14:17], v[234:237], v[226:229], v[14:17]
	v_mfma_f32_16x16x32_bf16 v[2:5], v[242:245], v[226:229], v[2:5]
	s_barrier
	s_add_i32 s47, s47, 2
	s_add_u32 s20, s20, 0x100
	s_addc_u32 s21, s21, 0
	s_add_u32 s45, s45, 0x100
	s_addc_u32 s46, s46, 0
	s_cmp_gt_u32 s47, 13
	s_cbranch_scc0 .LBB0_586
	v_pk_mul_f32 v[164:165], v[122:123], s[4:5] op_sel_hi:[1,0]
	v_pk_mul_f32 v[122:123], v[122:123], v[126:127]
	v_pk_mul_f32 v[126:127], v[114:115], s[4:5] op_sel_hi:[1,0]
	v_pk_mul_f32 v[114:115], v[114:115], v[118:119]
	v_exp_f32_e32 v126, v126
	v_exp_f32_e32 v127, v127
	v_pk_mul_f32 v[128:129], v[124:125], v[128:129]
	v_pk_mul_f32 v[124:125], v[124:125], s[4:5] op_sel_hi:[1,0]
	v_exp_f32_e32 v164, v164
	v_pk_add_f32 v[126:127], v[126:127], 1.0 op_sel_hi:[1,0]
	v_exp_f32_e32 v165, v165
	v_rcp_f32_e32 v126, v126
	v_rcp_f32_e32 v127, v127
	v_exp_f32_e32 v124, v124
	v_exp_f32_e32 v125, v125
	v_pk_add_f32 v[164:165], v[164:165], 1.0 op_sel_hi:[1,0]
	v_pk_mul_f32 v[118:119], v[126:127], v[114:115]
	v_pk_mul_f32 v[114:115], v[116:117], s[4:5] op_sel_hi:[1,0]
	v_pk_add_f32 v[124:125], v[124:125], 1.0 op_sel_hi:[1,0]
	v_exp_f32_e32 v114, v114
	v_exp_f32_e32 v115, v115
	v_rcp_f32_e32 v164, v164
	v_rcp_f32_e32 v165, v165
	v_rcp_f32_e32 v124, v124
	v_pk_add_f32 v[114:115], v[114:115], 1.0 op_sel_hi:[1,0]
	v_rcp_f32_e32 v125, v125
	v_rcp_f32_e32 v114, v114
	v_rcp_f32_e32 v115, v115
	v_lshl_or_b32 v140, s42, 7, v144
	v_ashrrev_i32_e32 v141, 31, v140
	v_lshl_add_u32 v162, s2, 8, v142
	v_lshl_add_u64 v[140:141], v[140:141], 1, s[14:15]
	v_pk_mul_f32 v[120:121], v[116:117], v[120:121]
	v_pk_mul_f32 v[122:123], v[164:165], v[122:123]
	v_pk_mul_f32 v[124:125], v[124:125], v[128:129]
	v_pk_mul_f32 v[120:121], v[114:115], v[120:121]
	v_mad_i64_i32 v[126:127], s[20:21], v162, s91, v[140:141]
	v_cvt_pk_bf16_f32 v114, v122, v123
	v_cvt_pk_bf16_f32 v115, v124, v125
	v_cvt_pk_bf16_f32 v116, v118, v119
	v_cvt_pk_bf16_f32 v117, v120, v121
	global_store_dwordx4 v[126:127], v[114:117], off
	v_pk_mul_f32 v[112:113], v[108:109], v[112:113]
	v_pk_mul_f32 v[108:109], v[108:109], s[4:5] op_sel_hi:[1,0]
	v_pk_mul_f32 v[114:115], v[106:107], s[4:5] op_sel_hi:[1,0]
	v_pk_mul_f32 v[106:107], v[106:107], v[110:111]
	v_pk_mul_f32 v[110:111], v[98:99], s[4:5] op_sel_hi:[1,0]
	v_pk_mul_f32 v[98:99], v[98:99], v[102:103]
	v_exp_f32_e32 v110, v110
	v_exp_f32_e32 v111, v111
	v_exp_f32_e32 v114, v114
	v_exp_f32_e32 v115, v115
	v_exp_f32_e32 v108, v108
	v_pk_add_f32 v[110:111], v[110:111], 1.0 op_sel_hi:[1,0]
	v_exp_f32_e32 v109, v109
	v_rcp_f32_e32 v110, v110
	v_rcp_f32_e32 v111, v111
	v_pk_add_f32 v[114:115], v[114:115], 1.0 op_sel_hi:[1,0]
	v_pk_add_f32 v[108:109], v[108:109], 1.0 op_sel_hi:[1,0]
	v_rcp_f32_e32 v114, v114
	v_pk_mul_f32 v[102:103], v[110:111], v[98:99]
	v_pk_mul_f32 v[98:99], v[100:101], s[4:5] op_sel_hi:[1,0]
	v_rcp_f32_e32 v115, v115
	v_exp_f32_e32 v98, v98
	v_exp_f32_e32 v99, v99
	v_rcp_f32_e32 v108, v108
	v_rcp_f32_e32 v109, v109
	v_or_b32_e32 v116, 16, v162
	v_pk_add_f32 v[98:99], v[98:99], 1.0 op_sel_hi:[1,0]
	v_pk_mul_f32 v[104:105], v[100:101], v[104:105]
	v_rcp_f32_e32 v98, v98
	v_rcp_f32_e32 v99, v99
	v_pk_mul_f32 v[106:107], v[114:115], v[106:107]
	v_pk_mul_f32 v[108:109], v[108:109], v[112:113]
	v_mad_i64_i32 v[110:111], s[20:21], v116, s91, v[140:141]
	v_pk_mul_f32 v[104:105], v[98:99], v[104:105]
	v_cvt_pk_bf16_f32 v98, v106, v107
	v_cvt_pk_bf16_f32 v99, v108, v109
	v_cvt_pk_bf16_f32 v100, v102, v103
	v_pk_mul_f32 v[96:97], v[92:93], v[96:97]
	v_cvt_pk_bf16_f32 v101, v104, v105
	global_store_dwordx4 v[110:111], v[98:101], off
	v_pk_mul_f32 v[92:93], v[92:93], s[4:5] op_sel_hi:[1,0]
	v_pk_mul_f32 v[88:89], v[84:85], v[88:89]
	v_pk_mul_f32 v[98:99], v[90:91], s[4:5] op_sel_hi:[1,0]
	v_pk_mul_f32 v[90:91], v[90:91], v[94:95]
	v_pk_mul_f32 v[94:95], v[82:83], s[4:5] op_sel_hi:[1,0]
	v_pk_mul_f32 v[82:83], v[82:83], v[86:87]
	v_exp_f32_e32 v94, v94
	v_exp_f32_e32 v95, v95
	v_exp_f32_e32 v98, v98
	v_exp_f32_e32 v99, v99
	v_exp_f32_e32 v92, v92
	v_pk_add_f32 v[94:95], v[94:95], 1.0 op_sel_hi:[1,0]
	v_exp_f32_e32 v93, v93
	v_rcp_f32_e32 v94, v94
	v_rcp_f32_e32 v95, v95
	v_pk_add_f32 v[98:99], v[98:99], 1.0 op_sel_hi:[1,0]
	v_pk_add_f32 v[92:93], v[92:93], 1.0 op_sel_hi:[1,0]
	v_rcp_f32_e32 v98, v98
	v_pk_mul_f32 v[86:87], v[94:95], v[82:83]
	v_pk_mul_f32 v[82:83], v[84:85], s[4:5] op_sel_hi:[1,0]
	v_rcp_f32_e32 v99, v99
	v_exp_f32_e32 v82, v82
	v_exp_f32_e32 v83, v83
	v_rcp_f32_e32 v92, v92
	v_rcp_f32_e32 v93, v93
	v_or_b32_e32 v100, 32, v162
	v_pk_add_f32 v[82:83], v[82:83], 1.0 op_sel_hi:[1,0]
	v_pk_mul_f32 v[90:91], v[98:99], v[90:91]
	v_rcp_f32_e32 v82, v82
	v_rcp_f32_e32 v83, v83
	v_pk_mul_f32 v[92:93], v[92:93], v[96:97]
	v_mad_i64_i32 v[94:95], s[20:21], v100, s91, v[140:141]
	v_pk_mul_f32 v[88:89], v[82:83], v[88:89]
	v_cvt_pk_bf16_f32 v82, v90, v91
	v_cvt_pk_bf16_f32 v83, v92, v93
	v_cvt_pk_bf16_f32 v84, v86, v87
	v_pk_mul_f32 v[80:81], v[76:77], v[80:81]
	v_cvt_pk_bf16_f32 v85, v88, v89
	global_store_dwordx4 v[94:95], v[82:85], off
	v_pk_mul_f32 v[76:77], v[76:77], s[4:5] op_sel_hi:[1,0]
	v_pk_mul_f32 v[72:73], v[68:69], v[72:73]
	v_pk_mul_f32 v[82:83], v[74:75], s[4:5] op_sel_hi:[1,0]
	v_pk_mul_f32 v[74:75], v[74:75], v[78:79]
	v_pk_mul_f32 v[78:79], v[66:67], s[4:5] op_sel_hi:[1,0]
	v_pk_mul_f32 v[66:67], v[66:67], v[70:71]
	v_exp_f32_e32 v78, v78
	v_exp_f32_e32 v79, v79
	v_exp_f32_e32 v82, v82
	v_exp_f32_e32 v83, v83
	v_exp_f32_e32 v76, v76
	v_pk_add_f32 v[78:79], v[78:79], 1.0 op_sel_hi:[1,0]
	v_exp_f32_e32 v77, v77
	v_rcp_f32_e32 v78, v78
	v_rcp_f32_e32 v79, v79
	v_pk_add_f32 v[82:83], v[82:83], 1.0 op_sel_hi:[1,0]
	v_pk_add_f32 v[76:77], v[76:77], 1.0 op_sel_hi:[1,0]
	v_rcp_f32_e32 v82, v82
	v_pk_mul_f32 v[70:71], v[78:79], v[66:67]
	v_pk_mul_f32 v[66:67], v[68:69], s[4:5] op_sel_hi:[1,0]
	v_rcp_f32_e32 v83, v83
	v_exp_f32_e32 v66, v66
	v_exp_f32_e32 v67, v67
	v_rcp_f32_e32 v76, v76
	v_rcp_f32_e32 v77, v77
	v_or_b32_e32 v84, 48, v162
	v_pk_add_f32 v[66:67], v[66:67], 1.0 op_sel_hi:[1,0]
	v_pk_mul_f32 v[74:75], v[82:83], v[74:75]
	v_rcp_f32_e32 v66, v66
	v_rcp_f32_e32 v67, v67
	v_pk_mul_f32 v[76:77], v[76:77], v[80:81]
	v_mad_i64_i32 v[78:79], s[20:21], v84, s91, v[140:141]
	v_pk_mul_f32 v[72:73], v[66:67], v[72:73]
	v_cvt_pk_bf16_f32 v66, v74, v75
	v_cvt_pk_bf16_f32 v67, v76, v77
	v_cvt_pk_bf16_f32 v68, v70, v71
	v_pk_mul_f32 v[64:65], v[60:61], v[64:65]
	v_cvt_pk_bf16_f32 v69, v72, v73
	global_store_dwordx4 v[78:79], v[66:69], off
	v_pk_mul_f32 v[60:61], v[60:61], s[4:5] op_sel_hi:[1,0]
	v_pk_mul_f32 v[56:57], v[52:53], v[56:57]
	v_pk_mul_f32 v[66:67], v[58:59], s[4:5] op_sel_hi:[1,0]
	v_pk_mul_f32 v[58:59], v[58:59], v[62:63]
	v_pk_mul_f32 v[62:63], v[50:51], s[4:5] op_sel_hi:[1,0]
	v_pk_mul_f32 v[50:51], v[50:51], v[54:55]
	v_exp_f32_e32 v62, v62
	v_exp_f32_e32 v63, v63
	v_exp_f32_e32 v66, v66
	v_exp_f32_e32 v67, v67
	v_exp_f32_e32 v60, v60
	v_pk_add_f32 v[62:63], v[62:63], 1.0 op_sel_hi:[1,0]
	v_exp_f32_e32 v61, v61
	v_rcp_f32_e32 v62, v62
	v_rcp_f32_e32 v63, v63
	v_pk_add_f32 v[66:67], v[66:67], 1.0 op_sel_hi:[1,0]
	v_pk_add_f32 v[60:61], v[60:61], 1.0 op_sel_hi:[1,0]
	v_rcp_f32_e32 v66, v66
	v_pk_mul_f32 v[54:55], v[62:63], v[50:51]
	v_pk_mul_f32 v[50:51], v[52:53], s[4:5] op_sel_hi:[1,0]
	v_rcp_f32_e32 v67, v67
	v_exp_f32_e32 v50, v50
	v_exp_f32_e32 v51, v51
	v_rcp_f32_e32 v60, v60
	v_rcp_f32_e32 v61, v61
	v_add_u32_e32 v68, 0x80, v162
	v_pk_add_f32 v[50:51], v[50:51], 1.0 op_sel_hi:[1,0]
	v_pk_mul_f32 v[58:59], v[66:67], v[58:59]
	v_rcp_f32_e32 v50, v50
	v_rcp_f32_e32 v51, v51
	v_pk_mul_f32 v[60:61], v[60:61], v[64:65]
	v_mad_i64_i32 v[62:63], s[20:21], v68, s91, v[140:141]
	v_pk_mul_f32 v[56:57], v[50:51], v[56:57]
	v_cvt_pk_bf16_f32 v50, v58, v59
	v_cvt_pk_bf16_f32 v51, v60, v61
	v_cvt_pk_bf16_f32 v52, v54, v55
	v_pk_mul_f32 v[48:49], v[44:45], v[48:49]
	v_cvt_pk_bf16_f32 v53, v56, v57
	global_store_dwordx4 v[62:63], v[50:53], off
	v_pk_mul_f32 v[44:45], v[44:45], s[4:5] op_sel_hi:[1,0]
	v_pk_mul_f32 v[40:41], v[36:37], v[40:41]
	v_pk_mul_f32 v[50:51], v[42:43], s[4:5] op_sel_hi:[1,0]
	v_pk_mul_f32 v[42:43], v[42:43], v[46:47]
	v_pk_mul_f32 v[46:47], v[34:35], s[4:5] op_sel_hi:[1,0]
	v_pk_mul_f32 v[34:35], v[34:35], v[38:39]
	v_exp_f32_e32 v46, v46
	v_exp_f32_e32 v47, v47
	v_exp_f32_e32 v50, v50
	v_exp_f32_e32 v51, v51
	v_exp_f32_e32 v44, v44
	v_pk_add_f32 v[46:47], v[46:47], 1.0 op_sel_hi:[1,0]
	v_exp_f32_e32 v45, v45
	v_rcp_f32_e32 v46, v46
	v_rcp_f32_e32 v47, v47
	v_pk_add_f32 v[50:51], v[50:51], 1.0 op_sel_hi:[1,0]
	v_pk_add_f32 v[44:45], v[44:45], 1.0 op_sel_hi:[1,0]
	v_rcp_f32_e32 v50, v50
	v_pk_mul_f32 v[38:39], v[46:47], v[34:35]
	v_pk_mul_f32 v[34:35], v[36:37], s[4:5] op_sel_hi:[1,0]
	v_rcp_f32_e32 v51, v51
	v_exp_f32_e32 v34, v34
	v_exp_f32_e32 v35, v35
	v_rcp_f32_e32 v44, v44
	v_rcp_f32_e32 v45, v45
	v_add_u32_e32 v52, 0x90, v162
	v_pk_add_f32 v[34:35], v[34:35], 1.0 op_sel_hi:[1,0]
	v_pk_mul_f32 v[42:43], v[50:51], v[42:43]
	v_rcp_f32_e32 v34, v34
	v_rcp_f32_e32 v35, v35
	v_pk_mul_f32 v[44:45], v[44:45], v[48:49]
	v_mad_i64_i32 v[46:47], s[20:21], v52, s91, v[140:141]
	v_pk_mul_f32 v[40:41], v[34:35], v[40:41]
	v_cvt_pk_bf16_f32 v34, v42, v43
	v_cvt_pk_bf16_f32 v35, v44, v45
	v_cvt_pk_bf16_f32 v36, v38, v39
	v_pk_mul_f32 v[32:33], v[28:29], v[32:33]
	v_cvt_pk_bf16_f32 v37, v40, v41
	global_store_dwordx4 v[46:47], v[34:37], off
	v_pk_mul_f32 v[28:29], v[28:29], s[4:5] op_sel_hi:[1,0]
	v_pk_mul_f32 v[24:25], v[20:21], v[24:25]
	v_pk_mul_f32 v[34:35], v[26:27], s[4:5] op_sel_hi:[1,0]
	v_pk_mul_f32 v[26:27], v[26:27], v[30:31]
	v_pk_mul_f32 v[30:31], v[18:19], s[4:5] op_sel_hi:[1,0]
	v_pk_mul_f32 v[18:19], v[18:19], v[22:23]
	v_exp_f32_e32 v30, v30
	v_exp_f32_e32 v31, v31
	v_exp_f32_e32 v34, v34
	v_exp_f32_e32 v35, v35
	v_exp_f32_e32 v28, v28
	v_pk_add_f32 v[30:31], v[30:31], 1.0 op_sel_hi:[1,0]
	v_exp_f32_e32 v29, v29
	v_rcp_f32_e32 v30, v30
	v_rcp_f32_e32 v31, v31
	v_pk_add_f32 v[34:35], v[34:35], 1.0 op_sel_hi:[1,0]
	v_pk_add_f32 v[28:29], v[28:29], 1.0 op_sel_hi:[1,0]
	v_rcp_f32_e32 v34, v34
	v_pk_mul_f32 v[22:23], v[30:31], v[18:19]
	v_pk_mul_f32 v[18:19], v[20:21], s[4:5] op_sel_hi:[1,0]
	v_rcp_f32_e32 v35, v35
	v_exp_f32_e32 v18, v18
	v_exp_f32_e32 v19, v19
	v_rcp_f32_e32 v28, v28
	v_rcp_f32_e32 v29, v29
	v_add_u32_e32 v36, 0xa0, v162
	v_pk_add_f32 v[18:19], v[18:19], 1.0 op_sel_hi:[1,0]
	v_pk_mul_f32 v[26:27], v[34:35], v[26:27]
	v_rcp_f32_e32 v18, v18
	v_rcp_f32_e32 v19, v19
	v_pk_mul_f32 v[28:29], v[28:29], v[32:33]
	v_mad_i64_i32 v[30:31], s[20:21], v36, s91, v[140:141]
	v_pk_mul_f32 v[24:25], v[18:19], v[24:25]
	v_cvt_pk_bf16_f32 v18, v26, v27
	v_cvt_pk_bf16_f32 v19, v28, v29
	v_cvt_pk_bf16_f32 v20, v22, v23
	v_pk_mul_f32 v[2:3], v[6:7], v[2:3]
	v_cvt_pk_bf16_f32 v21, v24, v25
	global_store_dwordx4 v[30:31], v[18:21], off
	v_pk_mul_f32 v[16:17], v[12:13], v[16:17]
	v_pk_mul_f32 v[12:13], v[12:13], s[4:5] op_sel_hi:[1,0]
	v_pk_mul_f32 v[18:19], v[10:11], s[4:5] op_sel_hi:[1,0]
	v_pk_mul_f32 v[10:11], v[10:11], v[14:15]
	v_pk_mul_f32 v[14:15], v[6:7], s[4:5] op_sel_hi:[1,0]
	v_exp_f32_e32 v18, v18
	v_exp_f32_e32 v14, v14
	v_exp_f32_e32 v15, v15
	v_exp_f32_e32 v19, v19
	v_exp_f32_e32 v12, v12
	v_exp_f32_e32 v13, v13
	v_pk_add_f32 v[14:15], v[14:15], 1.0 op_sel_hi:[1,0]
	v_pk_add_f32 v[18:19], v[18:19], 1.0 op_sel_hi:[1,0]
	v_rcp_f32_e32 v14, v14
	v_rcp_f32_e32 v15, v15
	v_pk_add_f32 v[12:13], v[12:13], 1.0 op_sel_hi:[1,0]
	v_rcp_f32_e32 v18, v18
	v_rcp_f32_e32 v19, v19
	v_pk_mul_f32 v[6:7], v[14:15], v[2:3]
	v_pk_mul_f32 v[2:3], v[8:9], s[4:5] op_sel_hi:[1,0]
	v_rcp_f32_e32 v12, v12
	v_exp_f32_e32 v2, v2
	v_exp_f32_e32 v3, v3
	v_rcp_f32_e32 v13, v13
	v_add_u32_e32 v20, 0xb0, v162
	v_mad_i64_i32 v[14:15], s[20:21], v20, s91, v[140:141]
	v_pk_add_f32 v[2:3], v[2:3], 1.0 op_sel_hi:[1,0]
	v_pk_mul_f32 v[4:5], v[8:9], v[4:5]
	v_rcp_f32_e32 v2, v2
	v_rcp_f32_e32 v3, v3
	s_and_b64 vcc, exec, s[38:39]
	s_mov_b32 s42, s0
	s_mov_b32 s2, s8
	s_mov_b64 s[22:23], s[18:19]
	s_mov_b64 s[20:21], s[16:17]
	v_pk_mul_f32 v[10:11], v[18:19], v[10:11]
	v_pk_mul_f32 v[12:13], v[12:13], v[16:17]
	v_pk_mul_f32 v[8:9], v[2:3], v[4:5]
	v_cvt_pk_bf16_f32 v2, v10, v11
	v_cvt_pk_bf16_f32 v3, v12, v13
	v_cvt_pk_bf16_f32 v4, v6, v7
	s_nop 0
	v_cvt_pk_bf16_f32 v5, v8, v9
	global_store_dwordx4 v[14:15], v[2:5], off
	s_cbranch_vccz .LBB0_579
	s_waitcnt vmcnt(0)
	s_cmpk_gt_u32 s26, 0xff
	s_cbranch_scc1 .LBB0_590
	s_barrier
